# conv epilogue of up-proj: 8 norm row-sum loads batched (counted vmcnt) + dead DPP zero-inits removed
# speedup vs baseline: 1.0792x; 1.0233x over previous
.LBB0_326:
	v_mov_b32_e32 v159, v225
	s_lshl_b32 s52, s44, 7
	v_ashrrev_i32_e32 v0, 7, v159
	v_and_b32_e32 v34, 0x7f, v159
	s_movk_i32 s2, 0x1600
	v_or_b32_e32 v54, s52, v34
	v_cmp_gt_i32_e32 vcc, 3, v0
	v_mul_lo_u32 v55, v0, s2
	v_mov_b32_e32 v34, s75
	v_mov_b32_e32 v35, s73
	s_sub_i32 s43, s42, 32
	v_cndmask_b32_e32 v0, 0, v55, vcc
	v_cndmask_b32_e32 v35, v34, v35, vcc
	v_mov_b32_e32 v34, s74
	v_mov_b32_e32 v36, s72
	s_lshr_b32 s2, s43, 3
	v_add_u32_e32 v0, v0, v54
	v_cndmask_b32_e32 v34, v34, v36, vcc
	s_add_i32 s2, s2, 1
	v_lshl_add_u64 v[36:37], v[0:1], 2, v[34:35]
	s_cmp_gt_i32 s42, 31
	global_load_dword v161, v[36:37], off
	v_add_u32_e32 v0, 0xb00, v55
	v_mov_b32_e32 v36, 0xb00
	s_cselect_b32 s2, s2, 0
	s_lshl_b32 s3, s42, 8
	v_and_b32_e32 v199, 15, v159
	v_cndmask_b32_e32 v0, v36, v0, vcc
	s_add_i32 s3, s3, s76
	v_add_u32_e32 v0, v0, v54
	v_or_b32_e32 v208, s3, v199
	v_lshl_add_u64 v[34:35], v[0:1], 2, v[34:35]
	v_ashrrev_i32_e32 v209, 31, v208
	global_load_dword v163, v[34:35], off
	v_lshl_add_u64 v[34:35], s[60:61], 0, v[208:209]
	v_lshl_add_u64 v[34:35], v[34:35], 4, s[56:57]
	global_load_dwordx4 v[54:57], v[34:35], off
	global_load_dwordx4 v[218:221], v[34:35], off offset:256
	global_load_dwordx4 v[228:231], v[34:35], off offset:512
	global_load_dwordx4 v[232:235], v[34:35], off offset:768
	global_load_dwordx4 v[240:243], v[34:35], off offset:2048
	global_load_dwordx4 v[244:247], v[34:35], off offset:2304
	global_load_dwordx4 v[248:251], v[34:35], off offset:2560
	global_load_dwordx4 v[34:37], v[34:35], off offset:2816
	v_lshrrev_b32_e32 v0, 1, v159
	v_and_or_b32 v206, v0, 24, s77
	s_mul_i32 s3, s18, 3
	s_add_u32 s46, s3, s2
	s_mul_hi_i32 s2, s18, 3
	s_addc_u32 s2, s2, 0
	s_mulk_i32 s2, 0x5800
	s_mul_hi_u32 s45, s46, 0x5800
	s_add_i32 s45, s45, s2
	s_lshl_b32 s2, s44, 8
	s_mulk_i32 s46, 0x5800
	s_ashr_i32 s3, s2, 31
	s_add_u32 s4, s87, s46
	s_addc_u32 s45, s88, s45
	s_lshl_b64 s[2:3], s[2:3], 2
	s_add_u32 s44, s4, s2
	s_addc_u32 s45, s45, s3
	v_lshlrev_b32_e32 v106, 2, v206
	v_cmp_lt_i32_e32 vcc, 14, v199
	s_mov_b64 s[46:47], 0
	s_waitcnt vmcnt(7)
	v_mov_b32_e32 v252, v55
	v_mov_b32_e32 v253, v56
	v_mov_b32_e32 v55, v57
	v_pk_add_f32 v[252:253], v[252:253], v[54:55]
	s_nop 0
	v_add_f32_e32 v252, v252, v253
	v_fmamk_f32 v252, v252, 0x3a800000, v223
	v_rsq_f32_e32 v0, v252
	s_waitcnt vmcnt(6)
	v_mov_b32_e32 v252, v219
	v_mov_b32_e32 v253, v220
	v_mov_b32_e32 v219, v221
	v_pk_add_f32 v[252:253], v[252:253], v[218:219]
	s_nop 0
	v_add_f32_e32 v252, v252, v253
	v_fmamk_f32 v252, v252, 0x3a800000, v223
	v_rsq_f32_e32 v202, v252
	s_waitcnt vmcnt(5)
	v_mov_b32_e32 v252, v229
	v_mov_b32_e32 v253, v230
	v_mov_b32_e32 v229, v231
	v_pk_add_f32 v[252:253], v[252:253], v[228:229]
	s_nop 0
	v_add_f32_e32 v252, v252, v253
	v_fmamk_f32 v252, v252, 0x3a800000, v223
	v_rsq_f32_e32 v204, v252
	s_waitcnt vmcnt(4)
	v_mov_b32_e32 v252, v233
	v_mov_b32_e32 v253, v234
	v_mov_b32_e32 v233, v235
	v_pk_add_f32 v[252:253], v[252:253], v[232:233]
	s_nop 0
	v_add_f32_e32 v252, v252, v253
	v_fmamk_f32 v252, v252, 0x3a800000, v223
	v_rsq_f32_e32 v158, v252
	s_waitcnt vmcnt(3)
	v_mov_b32_e32 v252, v241
	v_mov_b32_e32 v253, v242
	v_mov_b32_e32 v241, v243
	v_pk_add_f32 v[252:253], v[252:253], v[240:241]
	s_nop 0
	v_add_f32_e32 v252, v252, v253
	v_fmamk_f32 v252, v252, 0x3a800000, v223
	v_rsq_f32_e32 v160, v252
	s_waitcnt vmcnt(2)
	v_mov_b32_e32 v252, v245
	v_mov_b32_e32 v253, v246
	v_mov_b32_e32 v245, v247
	v_pk_add_f32 v[252:253], v[252:253], v[244:245]
	s_nop 0
	v_add_f32_e32 v252, v252, v253
	v_fmamk_f32 v252, v252, 0x3a800000, v223
	v_rsq_f32_e32 v198, v252
	s_waitcnt vmcnt(1)
	v_mov_b32_e32 v252, v249
	v_mov_b32_e32 v253, v250
	v_mov_b32_e32 v249, v251
	v_pk_add_f32 v[252:253], v[252:253], v[248:249]
	s_nop 0
	v_add_f32_e32 v252, v252, v253
	v_fmamk_f32 v252, v252, 0x3a800000, v223
	v_rsq_f32_e32 v200, v252
	s_waitcnt vmcnt(0)
	v_mov_b32_e32 v252, v35
	v_mov_b32_e32 v253, v36
	v_mov_b32_e32 v35, v37
	v_pk_add_f32 v[252:253], v[252:253], v[34:35]
	s_nop 0
	v_add_f32_e32 v252, v252, v253
	v_fmamk_f32 v252, v252, 0x3a800000, v223
	v_rsq_f32_e32 v162, v252
	global_load_dwordx4 v[54:57], v106, s[44:45] offset:16
	global_load_dwordx4 v[138:141], v106, s[44:45]
	global_load_dwordx4 v[34:37], v106, s[44:45] offset:528
	s_nop 0
	global_load_dwordx4 v[106:109], v106, s[44:45] offset:512
	s_and_saveexec_b64 s[44:45], vcc
	s_xor_b64 s[44:45], exec, s[44:45]
	s_mov_b64 s[46:47], exec
	s_or_saveexec_b64 s[44:45], s[44:45]
	s_waitcnt vmcnt(2)
	v_pk_fma_f32 v[144:145], v[144:145], v[158:159], v[140:141] op_sel_hi:[1,0,1]
	v_pk_fma_f32 v[142:143], v[142:143], v[158:159], v[138:139] op_sel_hi:[1,0,1]
	v_pk_fma_f32 v[152:153], v[88:89], v[0:1], v[140:141] op_sel_hi:[1,0,1]
	v_mov_b64_e32 v[156:157], v[144:145]
	v_pk_fma_f32 v[150:151], v[86:87], v[0:1], v[138:139] op_sel_hi:[1,0,1]
	v_mov_b32_e32 v164, s92
	v_cmp_eq_u32_e32 vcc, 0, v199
	v_mov_b64_e32 v[154:155], v[142:143]
	s_xor_b64 exec, exec, s[44:45]
	s_andn2_b64 s[46:47], s[46:47], exec
	s_and_b64 s[48:49], vcc, exec
	v_mov_b64_e32 v[156:157], v[152:153]
	v_mov_b32_e32 v164, s89
	s_or_b64 s[46:47], s[46:47], s[48:49]
	v_mov_b64_e32 v[154:155], v[150:151]
	s_or_b64 exec, exec, s[44:45]
	v_pk_fma_f32 v[88:89], v[52:53], v[0:1], v[56:57] op_sel_hi:[1,0,1]
	v_pk_fma_f32 v[86:87], v[50:51], v[0:1], v[54:55] op_sel_hi:[1,0,1]
	v_pk_fma_f32 v[84:85], v[84:85], v[158:159], v[56:57] op_sel_hi:[1,0,1]
	v_pk_fma_f32 v[82:83], v[82:83], v[158:159], v[54:55] op_sel_hi:[1,0,1]
	v_pk_fma_f32 v[132:133], v[132:133], v[160:161], v[140:141] op_sel_hi:[1,0,1]
	v_pk_fma_f32 v[130:131], v[130:131], v[160:161], v[138:139] op_sel_hi:[1,0,1]
	v_pk_fma_f32 v[52:53], v[136:137], v[160:161], v[56:57] op_sel_hi:[1,0,1]
	v_pk_fma_f32 v[50:51], v[134:135], v[160:161], v[54:55] op_sel_hi:[1,0,1]
	v_pk_fma_f32 v[120:121], v[120:121], v[162:163], v[140:141] op_sel_hi:[1,0,1]
	v_pk_fma_f32 v[118:119], v[118:119], v[162:163], v[138:139] op_sel_hi:[1,0,1]
	v_pk_fma_f32 v[48:49], v[48:49], v[162:163], v[56:57] op_sel_hi:[1,0,1]
	v_pk_fma_f32 v[46:47], v[46:47], v[162:163], v[54:55] op_sel_hi:[1,0,1]
	s_waitcnt vmcnt(0)
	v_pk_fma_f32 v[148:149], v[80:81], v[0:1], v[108:109] op_sel_hi:[1,0,1]
	v_pk_fma_f32 v[146:147], v[78:79], v[0:1], v[106:107] op_sel_hi:[1,0,1]
	v_pk_fma_f32 v[80:81], v[76:77], v[0:1], v[36:37] op_sel_hi:[1,0,1]
	v_pk_fma_f32 v[78:79], v[74:75], v[0:1], v[34:35] op_sel_hi:[1,0,1]
	v_pk_fma_f32 v[136:137], v[44:45], v[158:159], v[108:109] op_sel_hi:[1,0,1]
	v_pk_fma_f32 v[134:135], v[42:43], v[158:159], v[106:107] op_sel_hi:[1,0,1]
	v_pk_fma_f32 v[76:77], v[40:41], v[158:159], v[36:37] op_sel_hi:[1,0,1]
	v_pk_fma_f32 v[74:75], v[38:39], v[158:159], v[34:35] op_sel_hi:[1,0,1]
	v_pk_fma_f32 v[116:117], v[116:117], v[160:161], v[108:109] op_sel_hi:[1,0,1]
	v_pk_fma_f32 v[114:115], v[114:115], v[160:161], v[106:107] op_sel_hi:[1,0,1]
	v_pk_fma_f32 v[44:45], v[128:129], v[160:161], v[36:37] op_sel_hi:[1,0,1]
	v_pk_fma_f32 v[42:43], v[126:127], v[160:161], v[34:35] op_sel_hi:[1,0,1]
	v_pk_fma_f32 v[112:113], v[112:113], v[162:163], v[108:109] op_sel_hi:[1,0,1]
	v_pk_fma_f32 v[110:111], v[110:111], v[162:163], v[106:107] op_sel_hi:[1,0,1]
	v_pk_fma_f32 v[40:41], v[124:125], v[162:163], v[36:37] op_sel_hi:[1,0,1]
	v_pk_fma_f32 v[38:39], v[122:123], v[162:163], v[34:35] op_sel_hi:[1,0,1]
	s_and_saveexec_b64 s[44:45], s[46:47]
	s_cbranch_execz .LBB0_367
	v_mov_b64_e32 v[124:125], v[84:85]
	v_lshl_add_u32 v0, v206, 2, v164
	v_cmp_gt_i32_e32 vcc, 15, v199
	s_mov_b64 s[48:49], -1
	v_mov_b32_e32 v126, 0x410
	v_mov_b64_e32 v[122:123], v[82:83]
	ds_write_b128 v0, v[154:157]
	s_and_saveexec_b64 s[46:47], vcc
	s_cbranch_execz .LBB0_335
	v_cmp_eq_u32_e32 vcc, 0, v199
	s_mov_b64 s[48:49], 0
	v_mov_b32_e32 v126, 0x410
	s_and_saveexec_b64 s[50:51], vcc
	s_mov_b64 s[48:49], exec
	v_mov_b32_e32 v126, 16
	s_or_b64 exec, exec, s[50:51]
	v_mov_b64_e32 v[124:125], v[88:89]
	s_orn2_b64 s[48:49], s[48:49], exec
	v_mov_b64_e32 v[122:123], v[86:87]

.LBB0_377:
	v_pk_fma_f32 v[210:211], v[104:105], v[202:203], v[140:141] op_sel_hi:[1,0,1]
	v_pk_fma_f32 v[220:221], v[102:103], v[202:203], v[138:139] op_sel_hi:[1,0,1]
	v_pk_fma_f32 v[216:217], v[100:101], v[204:205], v[140:141] op_sel_hi:[1,0,1]
	v_pk_fma_f32 v[218:219], v[98:99], v[204:205], v[138:139] op_sel_hi:[1,0,1]
	v_mov_b32_dpp v247, v150 row_ror:1 row_mask:0xf bank_mask:0xf
	v_mov_b32_dpp v251, v151 row_ror:1 row_mask:0xf bank_mask:0xf
	v_mov_b32_dpp v238, v152 row_ror:1 row_mask:0xf bank_mask:0xf
	v_mov_b32_dpp v236, v153 row_ror:1 row_mask:0xf bank_mask:0xf
	v_mov_b32_dpp v212, v150 row_ror:15 row_mask:0xf bank_mask:0xf
	v_mov_b32_dpp v213, v151 row_ror:15 row_mask:0xf bank_mask:0xf
	v_mov_b32_dpp v214, v152 row_ror:15 row_mask:0xf bank_mask:0xf
	v_mov_b32_dpp v215, v153 row_ror:15 row_mask:0xf bank_mask:0xf
	v_mov_b32_dpp v231, v220 row_ror:15 row_mask:0xf bank_mask:0xf
	v_mov_b32_dpp v224, v221 row_ror:15 row_mask:0xf bank_mask:0xf
	v_mov_b32_dpp v229, v210 row_ror:15 row_mask:0xf bank_mask:0xf
	v_mov_b32_dpp v222, v211 row_ror:15 row_mask:0xf bank_mask:0xf
	v_mov_b32_dpp v245, v220 row_ror:1 row_mask:0xf bank_mask:0xf
	v_mov_b32_dpp v248, v221 row_ror:1 row_mask:0xf bank_mask:0xf
	v_mov_b32_dpp v252, v210 row_ror:1 row_mask:0xf bank_mask:0xf
	v_mov_b32_dpp v235, v211 row_ror:1 row_mask:0xf bank_mask:0xf
	v_mov_b32_dpp v250, v218 row_ror:15 row_mask:0xf bank_mask:0xf
	v_mov_b32_dpp v237, v219 row_ror:15 row_mask:0xf bank_mask:0xf
	v_mov_b32_dpp v234, v216 row_ror:15 row_mask:0xf bank_mask:0xf
	v_mov_b32_dpp v230, v217 row_ror:15 row_mask:0xf bank_mask:0xf
	v_mov_b32_dpp v0, v218 row_ror:1 row_mask:0xf bank_mask:0xf
	v_mov_b32_dpp v201, v219 row_ror:1 row_mask:0xf bank_mask:0xf
	v_mov_b32_dpp v242, v216 row_ror:1 row_mask:0xf bank_mask:0xf
	v_mov_b32_dpp v244, v217 row_ror:1 row_mask:0xf bank_mask:0xf
	v_mov_b32_dpp v241, v142 row_ror:15 row_mask:0xf bank_mask:0xf
	v_mov_b32_dpp v243, v143 row_ror:15 row_mask:0xf bank_mask:0xf
	v_mov_b32_dpp v246, v144 row_ror:15 row_mask:0xf bank_mask:0xf
	v_mov_b32_dpp v249, v145 row_ror:15 row_mask:0xf bank_mask:0xf
	v_mov_b32_dpp v253, v142 row_ror:1 row_mask:0xf bank_mask:0xf
	v_mov_b32_dpp v228, v143 row_ror:1 row_mask:0xf bank_mask:0xf
	v_mov_b32_dpp v232, v144 row_ror:1 row_mask:0xf bank_mask:0xf
	v_mov_b32_dpp v233, v145 row_ror:1 row_mask:0xf bank_mask:0xf
	ds_read_b128 v[126:129], v209 offset:2048
	ds_read_b128 v[122:125], v209 offset:2560
	ds_read_b128 v[102:105], v209 offset:3072
	ds_read_b128 v[98:101], v209 offset:3584
	v_mov_b32_e32 v154, 0
	s_and_b64 vcc, exec, s[46:47]
	v_mov_b32_e32 v178, 0
	v_mov_b32_e32 v179, 0
	v_mov_b32_e32 v180, 0
	v_mov_b32_e32 v181, 0
	s_cbranch_vccnz .LBB0_379
	v_lshl_add_u32 v155, v206, 2, s97
	ds_read_b128 v[178:181], v155

.LBB0_381:
	v_cmp_eq_u32_e64 s[42:43], 0, v199
	v_cmp_eq_u32_e64 s[44:45], 15, v199
	s_movk_i32 s2, 0xb00
	s_waitcnt lgkmcnt(4)
	v_cndmask_b32_e64 v185, v236, v185, s[42:43]
	v_cndmask_b32_e64 v184, v238, v184, s[42:43]
	v_cndmask_b32_e64 v183, v251, v183, s[42:43]
	v_cndmask_b32_e64 v182, v247, v182, s[42:43]
	v_pk_mul_f32 v[184:185], v[172:173], v[184:185]
	v_cndmask_b32_e64 v215, v215, v222, s[44:45]
	v_cndmask_b32_e64 v214, v214, v229, s[44:45]
	v_pk_mul_f32 v[182:183], v[170:171], v[182:183]
	v_pk_fma_f32 v[152:153], v[152:153], v[168:169], v[184:185]
	v_cndmask_b32_e64 v213, v213, v224, s[44:45]
	v_cndmask_b32_e64 v212, v212, v231, s[44:45]
	v_pk_fma_f32 v[150:151], v[150:151], v[166:167], v[182:183]
	v_pk_fma_f32 v[152:153], v[164:165], v[214:215], v[152:153]
	v_pk_fma_f32 v[150:151], v[162:163], v[212:213], v[150:151]
	v_pk_add_f32 v[212:213], v[160:161], v[152:153]
	v_cndmask_b32_e64 v153, v248, v251, s[42:43]
	v_cndmask_b32_e64 v152, v245, v247, s[42:43]
	v_pk_add_f32 v[214:215], v[158:159], v[150:151]
	v_cndmask_b32_e64 v151, v235, v236, s[42:43]
	v_cndmask_b32_e64 v150, v252, v238, s[42:43]
	v_pk_mul_f32 v[152:153], v[170:171], v[152:153]
	v_cndmask_b32_e64 v185, v224, v237, s[44:45]
	v_cndmask_b32_e64 v184, v231, v250, s[44:45]
	v_pk_mul_f32 v[150:151], v[172:173], v[150:151]
	v_pk_fma_f32 v[152:153], v[220:221], v[166:167], v[152:153]
	v_cndmask_b32_e64 v183, v222, v230, s[44:45]
	v_cndmask_b32_e64 v182, v229, v234, s[44:45]
	v_pk_fma_f32 v[150:151], v[210:211], v[168:169], v[150:151]
	v_pk_fma_f32 v[152:153], v[162:163], v[184:185], v[152:153]
	v_pk_fma_f32 v[150:151], v[164:165], v[182:183], v[150:151]
	v_pk_add_f32 v[210:211], v[158:159], v[152:153]
	v_cndmask_b32_e64 v153, v201, v248, s[42:43]
	v_cndmask_b32_e64 v152, v0, v245, s[42:43]
	v_pk_add_f32 v[184:185], v[160:161], v[150:151]
	v_cndmask_b32_e64 v151, v244, v235, s[42:43]
	v_cndmask_b32_e64 v150, v242, v252, s[42:43]
	v_pk_mul_f32 v[152:153], v[170:171], v[152:153]
	v_cndmask_b32_e64 v221, v237, v243, s[44:45]
	v_cndmask_b32_e64 v220, v250, v241, s[44:45]
	v_pk_mul_f32 v[150:151], v[172:173], v[150:151]
	v_pk_fma_f32 v[152:153], v[218:219], v[166:167], v[152:153]
	v_cndmask_b32_e64 v183, v230, v249, s[44:45]
	v_cndmask_b32_e64 v182, v234, v246, s[44:45]
	v_pk_fma_f32 v[150:151], v[216:217], v[168:169], v[150:151]
	v_pk_fma_f32 v[216:217], v[162:163], v[220:221], v[152:153]
	v_pk_fma_f32 v[150:151], v[164:165], v[182:183], v[150:151]
	v_pk_add_f32 v[182:183], v[158:159], v[216:217]
	v_cndmask_b32_e64 v217, v228, v201, s[42:43]
	v_cndmask_b32_e64 v216, v253, v0, s[42:43]
	v_pk_add_f32 v[152:153], v[160:161], v[150:151]
	v_cndmask_b32_e64 v151, v233, v244, s[42:43]
	v_cndmask_b32_e64 v150, v232, v242, s[42:43]
	v_pk_mul_f32 v[170:171], v[170:171], v[216:217]
	v_cndmask_b32_e64 v175, v243, v175, s[44:45]
	v_cndmask_b32_e64 v174, v241, v174, s[44:45]
	v_pk_mul_f32 v[150:151], v[172:173], v[150:151]
	v_pk_fma_f32 v[142:143], v[142:143], v[166:167], v[170:171]
	v_cndmask_b32_e64 v177, v249, v177, s[44:45]
	v_cndmask_b32_e64 v176, v246, v176, s[44:45]
	v_pk_fma_f32 v[144:145], v[144:145], v[168:169], v[150:151]
	v_pk_fma_f32 v[150:151], v[162:163], v[174:175], v[142:143]
	v_or_b32_e32 v0, s52, v206
	v_pk_fma_f32 v[142:143], v[164:165], v[176:177], v[144:145]
	v_pk_add_f32 v[144:145], v[158:159], v[150:151]
	v_mad_u64_u32 v[150:151], s[2:3], v208, s2, v[0:1]
	v_mov_b32_e32 v158, v202
	v_mov_b32_e32 v159, v202
	v_mov_b32_e32 v203, v202
	v_pk_fma_f32 v[96:97], v[96:97], v[158:159], v[108:109]
	v_mov_b32_e32 v158, v204
	v_mov_b32_e32 v159, v204
	v_mov_b32_dpp v0, v146 row_ror:1 row_mask:0xf bank_mask:0xf
	v_mov_b32_dpp v151, v147 row_ror:1 row_mask:0xf bank_mask:0xf
	v_mov_b32_dpp v166, v148 row_ror:1 row_mask:0xf bank_mask:0xf
	v_mov_b32_dpp v167, v149 row_ror:1 row_mask:0xf bank_mask:0xf
	v_pk_add_f32 v[142:143], v[160:161], v[142:143]
	v_pk_fma_f32 v[94:95], v[94:95], v[202:203], v[106:107]
	v_pk_fma_f32 v[92:93], v[92:93], v[158:159], v[108:109]
	s_waitcnt lgkmcnt(0)
	v_cndmask_b32_e64 v159, v167, v181, s[42:43]
	v_cndmask_b32_e64 v158, v166, v180, s[42:43]
	v_cndmask_b32_e64 v161, v151, v179, s[42:43]
	v_cndmask_b32_e64 v160, v0, v178, s[42:43]
	v_mov_b32_dpp v164, v146 row_ror:15 row_mask:0xf bank_mask:0xf
	v_mov_b32_dpp v165, v147 row_ror:15 row_mask:0xf bank_mask:0xf
	v_mov_b32_dpp v162, v148 row_ror:15 row_mask:0xf bank_mask:0xf
	v_mov_b32_dpp v163, v149 row_ror:15 row_mask:0xf bank_mask:0xf
	v_mov_b32_dpp v168, v94 row_ror:15 row_mask:0xf bank_mask:0xf
	v_mov_b32_dpp v169, v95 row_ror:15 row_mask:0xf bank_mask:0xf
	v_mov_b32_dpp v170, v96 row_ror:15 row_mask:0xf bank_mask:0xf
	v_mov_b32_dpp v171, v97 row_ror:15 row_mask:0xf bank_mask:0xf
	v_pk_mul_f32 v[160:161], v[126:127], v[160:161]
	v_pk_mul_f32 v[158:159], v[128:129], v[158:159]
	v_cndmask_b32_e64 v163, v163, v171, s[44:45]
	v_cndmask_b32_e64 v162, v162, v170, s[44:45]
	v_cndmask_b32_e64 v165, v165, v169, s[44:45]
	v_cndmask_b32_e64 v164, v164, v168, s[44:45]
	v_pk_fma_f32 v[148:149], v[148:149], v[124:125], v[158:159]
	v_pk_fma_f32 v[146:147], v[146:147], v[122:123], v[160:161]
	v_mov_b32_e32 v205, v204
	v_pk_fma_f32 v[146:147], v[102:103], v[164:165], v[146:147]
	v_pk_fma_f32 v[148:149], v[104:105], v[162:163], v[148:149]
	v_mov_b32_dpp v172, v94 row_ror:1 row_mask:0xf bank_mask:0xf
	v_mov_b32_dpp v173, v95 row_ror:1 row_mask:0xf bank_mask:0xf
	v_mov_b32_dpp v174, v96 row_ror:1 row_mask:0xf bank_mask:0xf
	v_mov_b32_dpp v175, v97 row_ror:1 row_mask:0xf bank_mask:0xf
	v_pk_fma_f32 v[90:91], v[90:91], v[204:205], v[106:107]
	v_pk_add_f32 v[158:159], v[100:101], v[148:149]
	v_pk_add_f32 v[160:161], v[98:99], v[146:147]
	v_cndmask_b32_e64 v147, v175, v167, s[42:43]
	v_cndmask_b32_e64 v146, v174, v166, s[42:43]
	v_cndmask_b32_e64 v149, v173, v151, s[42:43]
	v_cndmask_b32_e64 v148, v172, v0, s[42:43]
	v_mov_b32_dpp v176, v90 row_ror:15 row_mask:0xf bank_mask:0xf
	v_mov_b32_dpp v177, v91 row_ror:15 row_mask:0xf bank_mask:0xf
	v_mov_b32_dpp v178, v92 row_ror:15 row_mask:0xf bank_mask:0xf
	v_mov_b32_dpp v179, v93 row_ror:15 row_mask:0xf bank_mask:0xf
	v_pk_mul_f32 v[146:147], v[128:129], v[146:147]
	v_pk_mul_f32 v[148:149], v[126:127], v[148:149]
	v_cndmask_b32_e64 v163, v171, v179, s[44:45]
	v_cndmask_b32_e64 v162, v170, v178, s[44:45]
	v_cndmask_b32_e64 v165, v169, v177, s[44:45]
	v_cndmask_b32_e64 v164, v168, v176, s[44:45]
	v_pk_fma_f32 v[96:97], v[96:97], v[124:125], v[146:147]
	v_pk_fma_f32 v[94:95], v[94:95], v[122:123], v[148:149]
	v_pk_fma_f32 v[96:97], v[104:105], v[162:163], v[96:97]
	v_pk_fma_f32 v[94:95], v[102:103], v[164:165], v[94:95]
	v_mov_b32_dpp v0, v90 row_ror:1 row_mask:0xf bank_mask:0xf
	v_mov_b32_dpp v151, v91 row_ror:1 row_mask:0xf bank_mask:0xf
	v_mov_b32_dpp v166, v92 row_ror:1 row_mask:0xf bank_mask:0xf
	v_mov_b32_dpp v167, v93 row_ror:1 row_mask:0xf bank_mask:0xf
	v_pk_add_f32 v[146:147], v[100:101], v[96:97]
	v_pk_add_f32 v[148:149], v[98:99], v[94:95]
	v_cndmask_b32_e64 v95, v167, v175, s[42:43]
	v_cndmask_b32_e64 v94, v166, v174, s[42:43]
	v_cndmask_b32_e64 v97, v151, v173, s[42:43]
	v_cndmask_b32_e64 v96, v0, v172, s[42:43]
	v_mov_b32_dpp v168, v134 row_ror:15 row_mask:0xf bank_mask:0xf
	v_mov_b32_dpp v169, v135 row_ror:15 row_mask:0xf bank_mask:0xf
	v_mov_b32_dpp v170, v136 row_ror:15 row_mask:0xf bank_mask:0xf
	v_mov_b32_dpp v171, v137 row_ror:15 row_mask:0xf bank_mask:0xf
	v_pk_mul_f32 v[94:95], v[128:129], v[94:95]
	v_pk_mul_f32 v[96:97], v[126:127], v[96:97]
	v_cndmask_b32_e64 v163, v179, v171, s[44:45]
	v_cndmask_b32_e64 v162, v178, v170, s[44:45]
	v_cndmask_b32_e64 v165, v177, v169, s[44:45]
	v_cndmask_b32_e64 v164, v176, v168, s[44:45]
	v_pk_fma_f32 v[92:93], v[92:93], v[124:125], v[94:95]
	v_pk_fma_f32 v[90:91], v[90:91], v[122:123], v[96:97]
	v_pk_fma_f32 v[92:93], v[104:105], v[162:163], v[92:93]
	v_pk_fma_f32 v[90:91], v[102:103], v[164:165], v[90:91]
	v_pk_add_f32 v[94:95], v[100:101], v[92:93]
	v_pk_add_f32 v[96:97], v[98:99], v[90:91]
	v_mov_b32_dpp v92, v134 row_ror:1 row_mask:0xf bank_mask:0xf
	v_mov_b32_dpp v93, v135 row_ror:1 row_mask:0xf bank_mask:0xf
	v_mov_b32_dpp v90, v136 row_ror:1 row_mask:0xf bank_mask:0xf
	v_mov_b32_dpp v91, v137 row_ror:1 row_mask:0xf bank_mask:0xf
	v_cndmask_b32_e64 v91, v91, v167, s[42:43]
	v_cndmask_b32_e64 v90, v90, v166, s[42:43]
	v_cndmask_b32_e64 v93, v93, v151, s[42:43]
	v_cndmask_b32_e64 v92, v92, v0, s[42:43]
	v_pk_mul_f32 v[90:91], v[128:129], v[90:91]
	v_pk_mul_f32 v[92:93], v[126:127], v[92:93]
	v_cndmask_b32_e64 v157, v171, v157, s[44:45]
	v_cndmask_b32_e64 v156, v170, v156, s[44:45]
	v_cndmask_b32_e64 v155, v169, v155, s[44:45]
	v_cndmask_b32_e64 v154, v168, v154, s[44:45]
	v_pk_fma_f32 v[90:91], v[136:137], v[124:125], v[90:91]
	v_pk_fma_f32 v[92:93], v[134:135], v[122:123], v[92:93]
	v_pk_fma_f32 v[90:91], v[104:105], v[156:157], v[90:91]
	v_pk_fma_f32 v[92:93], v[102:103], v[154:155], v[92:93]
	v_pk_add_f32 v[90:91], v[100:101], v[90:91]
	v_pk_add_f32 v[92:93], v[98:99], v[92:93]
	v_mul_f32_e32 v0, 0xbfb8aa3b, v214
	v_mul_f32_e32 v98, 0xbfb8aa3b, v215
	v_exp_f32_e32 v0, v0
	v_exp_f32_e32 v98, v98
	v_mul_f32_e32 v99, 0xbfb8aa3b, v212
	v_mul_f32_e32 v100, 0xbfb8aa3b, v213
	v_exp_f32_e32 v99, v99
	v_exp_f32_e32 v100, v100
	v_add_f32_e32 v0, 1.0, v0
	v_add_f32_e32 v98, 1.0, v98
	v_rcp_f32_e32 v0, v0
	v_rcp_f32_e32 v98, v98
	v_add_f32_e32 v99, 1.0, v99
	v_add_f32_e32 v100, 1.0, v100
	v_rcp_f32_e32 v99, v99
	v_rcp_f32_e32 v100, v100
	v_mul_f32_e32 v0, v214, v0
	v_mul_f32_e32 v98, v215, v98
	v_mul_f32_e32 v0, v0, v160
	v_mul_f32_e32 v98, v98, v161
	v_mul_f32_e32 v99, v212, v99
	v_mul_f32_e32 v100, v213, v100
	v_mul_f32_e32 v99, v99, v158
	v_mul_f32_e32 v100, v100, v159
	v_cvt_pk_bf16_f32 v98, v0, v98
	v_mov_b32_e32 v0, v150
	v_cvt_pk_bf16_f32 v99, v99, v100
	s_nop 0
	v_lshl_add_u64 v[100:101], v[0:1], 1, s[62:63]
	global_store_dwordx2 v[100:101], v[98:99], off
	v_mul_f32_e32 v0, 0xbfb8aa3b, v210
	v_mul_f32_e32 v98, 0xbfb8aa3b, v211
	v_exp_f32_e32 v0, v0
	v_exp_f32_e32 v98, v98
	v_mul_f32_e32 v99, 0xbfb8aa3b, v184
	v_exp_f32_e32 v99, v99
	v_mul_f32_e32 v100, 0xbfb8aa3b, v185
	v_exp_f32_e32 v100, v100
	v_add_f32_e32 v0, 1.0, v0
	v_add_f32_e32 v98, 1.0, v98
	v_rcp_f32_e32 v0, v0
	v_rcp_f32_e32 v98, v98
	v_add_f32_e32 v99, 1.0, v99
	v_rcp_f32_e32 v99, v99
	v_add_f32_e32 v100, 1.0, v100
	v_rcp_f32_e32 v100, v100
	v_mul_f32_e32 v0, v210, v0
	v_mul_f32_e32 v98, v211, v98
	v_mul_f32_e32 v0, v0, v148
	v_mul_f32_e32 v98, v98, v149
	v_mul_f32_e32 v99, v184, v99
	v_mul_f32_e32 v99, v99, v146
	v_mul_f32_e32 v100, v185, v100
	v_cvt_pk_bf16_f32 v98, v0, v98
	v_mov_b32_e32 v0, v150
	v_mul_f32_e32 v100, v100, v147
	v_cvt_pk_bf16_f32 v99, v99, v100
	s_nop 0
	v_add_u32_e32 v0, 0xb000, v0
	v_lshl_add_u64 v[100:101], v[0:1], 1, s[62:63]
	v_mul_f32_e32 v0, 0xbfb8aa3b, v182
	v_exp_f32_e32 v0, v0
	global_store_dwordx2 v[100:101], v[98:99], off
	v_add_f32_e32 v0, 1.0, v0
	v_rcp_f32_e32 v0, v0
	s_nop 0
	v_mul_f32_e32 v0, v182, v0
	v_mul_f32_e32 v0, v0, v96
	v_mul_f32_e32 v96, 0xbfb8aa3b, v183
	v_exp_f32_e32 v96, v96
	s_nop 0
	v_add_f32_e32 v96, 1.0, v96
	v_rcp_f32_e32 v96, v96
	s_nop 0
	v_mul_f32_e32 v96, v183, v96
	v_mul_f32_e32 v96, v96, v97
	v_mul_f32_e32 v97, 0xbfb8aa3b, v152
	v_exp_f32_e32 v97, v97
	s_nop 0
	v_add_f32_e32 v97, 1.0, v97
	v_rcp_f32_e32 v97, v97
	s_nop 0
	v_mul_f32_e32 v97, v152, v97
	v_mul_f32_e32 v97, v97, v94
	v_mul_f32_e32 v94, 0xbfb8aa3b, v153
	v_exp_f32_e32 v94, v94
	s_nop 0
	v_add_f32_e32 v94, 1.0, v94
	v_rcp_f32_e32 v94, v94
	s_nop 0
	v_mul_f32_e32 v94, v153, v94
	v_mul_f32_e32 v95, v94, v95
	v_cvt_pk_bf16_f32 v94, v0, v96
	v_mov_b32_e32 v0, v150
	v_cvt_pk_bf16_f32 v95, v97, v95
	s_nop 0
	v_add_u32_e32 v0, 0x16000, v0
	v_lshl_add_u64 v[96:97], v[0:1], 1, s[62:63]
	v_mul_f32_e32 v0, 0xbfb8aa3b, v144
	v_exp_f32_e32 v0, v0
	global_store_dwordx2 v[96:97], v[94:95], off
	v_add_f32_e32 v0, 1.0, v0
	v_rcp_f32_e32 v0, v0
	s_nop 0
	v_mul_f32_e32 v0, v144, v0
	v_mul_f32_e32 v0, v0, v92
	v_mul_f32_e32 v92, 0xbfb8aa3b, v145
	v_exp_f32_e32 v92, v92
	s_nop 0
	v_add_f32_e32 v92, 1.0, v92
	v_rcp_f32_e32 v92, v92
	s_nop 0
	v_mul_f32_e32 v92, v145, v92
	v_mul_f32_e32 v92, v92, v93
	v_mul_f32_e32 v93, 0xbfb8aa3b, v142
	v_exp_f32_e32 v93, v93
	s_nop 0
	v_add_f32_e32 v93, 1.0, v93
	v_rcp_f32_e32 v93, v93
	s_nop 0
	v_mul_f32_e32 v93, v142, v93
	v_mul_f32_e32 v93, v93, v90
	v_mul_f32_e32 v90, 0xbfb8aa3b, v143
	v_exp_f32_e32 v90, v90
	s_nop 0
	v_add_f32_e32 v90, 1.0, v90
	v_rcp_f32_e32 v90, v90
	s_nop 0
	v_mul_f32_e32 v90, v143, v90
	v_mul_f32_e32 v91, v90, v91
	v_cvt_pk_bf16_f32 v90, v0, v92
	v_mov_b32_e32 v0, v150
	v_cvt_pk_bf16_f32 v91, v93, v91
	s_nop 0
	v_add_u32_e32 v0, 0x21000, v0
	v_lshl_add_u64 v[92:93], v[0:1], 1, s[62:63]
	global_store_dwordx2 v[92:93], v[90:91], off
	ds_read_b128 v[134:137], v209
	ds_read_b128 v[126:129], v209 offset:512
	ds_read_b128 v[122:125], v209 offset:1024
	ds_read_b128 v[102:105], v209 offset:1536
	v_cndmask_b32_e64 v0, 0, 1, s[36:37]
	v_mov_b32_e32 v142, 0
	v_cmp_ne_u32_e64 s[50:51], 1, v0
	s_andn2_b64 vcc, exec, s[36:37]
	v_mov_b32_e32 v146, 0
	v_mov_b32_e32 v147, 0
	v_mov_b32_e32 v148, 0
	v_mov_b32_e32 v149, 0
	s_cbranch_vccnz .LBB0_383
	ds_read_b128 v[146:149], v240 offset:3072

.LBB0_385:
	v_pk_fma_f32 v[160:161], v[72:73], v[198:199], v[140:141] op_sel_hi:[1,0,1]
	v_pk_fma_f32 v[162:163], v[70:71], v[198:199], v[138:139] op_sel_hi:[1,0,1]
	v_pk_fma_f32 v[156:157], v[68:69], v[200:201], v[140:141] op_sel_hi:[1,0,1]
	v_pk_fma_f32 v[158:159], v[66:67], v[200:201], v[138:139] op_sel_hi:[1,0,1]
	v_mov_b32_dpp v170, v130 row_ror:1 row_mask:0xf bank_mask:0xf
	v_mov_b32_dpp v174, v131 row_ror:1 row_mask:0xf bank_mask:0xf
	v_mov_b32_dpp v178, v132 row_ror:1 row_mask:0xf bank_mask:0xf
	v_mov_b32_dpp v182, v133 row_ror:1 row_mask:0xf bank_mask:0xf
	v_mov_b32_dpp v152, v130 row_ror:15 row_mask:0xf bank_mask:0xf
	v_mov_b32_dpp v153, v131 row_ror:15 row_mask:0xf bank_mask:0xf
	v_mov_b32_dpp v154, v132 row_ror:15 row_mask:0xf bank_mask:0xf
	v_mov_b32_dpp v155, v133 row_ror:15 row_mask:0xf bank_mask:0xf
	v_mov_b32_dpp v185, v162 row_ror:15 row_mask:0xf bank_mask:0xf
	v_mov_b32_dpp v208, v163 row_ror:15 row_mask:0xf bank_mask:0xf
	v_mov_b32_dpp v210, v160 row_ror:15 row_mask:0xf bank_mask:0xf
	v_mov_b32_dpp v211, v161 row_ror:15 row_mask:0xf bank_mask:0xf
	v_mov_b32_dpp v168, v162 row_ror:1 row_mask:0xf bank_mask:0xf
	v_mov_b32_dpp v171, v163 row_ror:1 row_mask:0xf bank_mask:0xf
	v_mov_b32_dpp v175, v160 row_ror:1 row_mask:0xf bank_mask:0xf
	v_mov_b32_dpp v179, v161 row_ror:1 row_mask:0xf bank_mask:0xf
	v_mov_b32_dpp v173, v158 row_ror:15 row_mask:0xf bank_mask:0xf
	v_mov_b32_dpp v177, v159 row_ror:15 row_mask:0xf bank_mask:0xf
	v_mov_b32_dpp v181, v156 row_ror:15 row_mask:0xf bank_mask:0xf
	v_mov_b32_dpp v184, v157 row_ror:15 row_mask:0xf bank_mask:0xf
	v_mov_b32_dpp v0, v158 row_ror:1 row_mask:0xf bank_mask:0xf
	v_mov_b32_dpp v151, v159 row_ror:1 row_mask:0xf bank_mask:0xf
	v_mov_b32_dpp v165, v156 row_ror:1 row_mask:0xf bank_mask:0xf
	v_mov_b32_dpp v167, v157 row_ror:1 row_mask:0xf bank_mask:0xf
	v_mov_b32_dpp v164, v118 row_ror:15 row_mask:0xf bank_mask:0xf
	v_mov_b32_dpp v166, v119 row_ror:15 row_mask:0xf bank_mask:0xf
	v_mov_b32_dpp v169, v120 row_ror:15 row_mask:0xf bank_mask:0xf
	v_mov_b32_dpp v172, v121 row_ror:15 row_mask:0xf bank_mask:0xf
	v_mov_b32_dpp v176, v118 row_ror:1 row_mask:0xf bank_mask:0xf
	v_mov_b32_dpp v180, v119 row_ror:1 row_mask:0xf bank_mask:0xf
	v_mov_b32_dpp v183, v120 row_ror:1 row_mask:0xf bank_mask:0xf
	v_mov_b32_dpp v206, v121 row_ror:1 row_mask:0xf bank_mask:0xf
	ds_read_b128 v[94:97], v209 offset:2048
	ds_read_b128 v[90:93], v209 offset:2560
	ds_read_b128 v[70:73], v209 offset:3072
	ds_read_b128 v[66:69], v209 offset:3584
	v_mov_b32_e32 v98, 0
	s_and_b64 vcc, exec, s[50:51]
	v_mov_b32_e32 v138, 0
	v_mov_b32_e32 v139, 0
	v_mov_b32_e32 v140, 0
	v_mov_b32_e32 v141, 0
	s_cbranch_vccnz .LBB0_387
	ds_read_b128 v[138:141], v240 offset:3584

.LBB0_389:
	s_waitcnt lgkmcnt(4)
	v_cndmask_b32_e64 v149, v182, v149, s[42:43]
	v_cndmask_b32_e64 v148, v178, v148, s[42:43]
	v_cndmask_b32_e64 v147, v174, v147, s[42:43]
	v_cndmask_b32_e64 v146, v170, v146, s[42:43]
	v_pk_mul_f32 v[148:149], v[136:137], v[148:149]
	v_cndmask_b32_e64 v155, v155, v211, s[44:45]
	v_cndmask_b32_e64 v154, v154, v210, s[44:45]
	v_pk_mul_f32 v[146:147], v[134:135], v[146:147]
	v_pk_fma_f32 v[132:133], v[132:133], v[128:129], v[148:149]
	v_cndmask_b32_e64 v153, v153, v208, s[44:45]
	v_cndmask_b32_e64 v152, v152, v185, s[44:45]
	v_pk_fma_f32 v[130:131], v[130:131], v[126:127], v[146:147]
	v_pk_fma_f32 v[132:133], v[124:125], v[154:155], v[132:133]
	v_pk_fma_f32 v[130:131], v[122:123], v[152:153], v[130:131]
	v_pk_add_f32 v[152:153], v[104:105], v[132:133]
	v_cndmask_b32_e64 v133, v171, v174, s[42:43]
	v_cndmask_b32_e64 v132, v168, v170, s[42:43]
	v_pk_add_f32 v[154:155], v[102:103], v[130:131]
	v_cndmask_b32_e64 v131, v179, v182, s[42:43]
	v_cndmask_b32_e64 v130, v175, v178, s[42:43]
	v_pk_mul_f32 v[132:133], v[134:135], v[132:133]
	v_cndmask_b32_e64 v149, v208, v177, s[44:45]
	v_cndmask_b32_e64 v148, v185, v173, s[44:45]
	v_pk_mul_f32 v[130:131], v[136:137], v[130:131]
	v_pk_fma_f32 v[132:133], v[162:163], v[126:127], v[132:133]
	v_cndmask_b32_e64 v147, v211, v184, s[44:45]
	v_cndmask_b32_e64 v146, v210, v181, s[44:45]
	v_pk_fma_f32 v[130:131], v[160:161], v[128:129], v[130:131]
	v_pk_fma_f32 v[132:133], v[122:123], v[148:149], v[132:133]
	v_pk_fma_f32 v[130:131], v[124:125], v[146:147], v[130:131]
	v_pk_add_f32 v[148:149], v[102:103], v[132:133]
	v_cndmask_b32_e64 v133, v151, v171, s[42:43]
	v_cndmask_b32_e64 v132, v0, v168, s[42:43]
	v_pk_add_f32 v[146:147], v[104:105], v[130:131]
	v_cndmask_b32_e64 v131, v167, v179, s[42:43]
	v_cndmask_b32_e64 v130, v165, v175, s[42:43]
	v_pk_mul_f32 v[132:133], v[134:135], v[132:133]
	v_pk_mul_f32 v[130:131], v[136:137], v[130:131]
	v_pk_fma_f32 v[132:133], v[158:159], v[126:127], v[132:133]
	v_cndmask_b32_e64 v159, v180, v151, s[42:43]
	v_cndmask_b32_e64 v158, v176, v0, s[42:43]
	v_pk_fma_f32 v[130:131], v[156:157], v[128:129], v[130:131]
	v_cndmask_b32_e64 v157, v206, v167, s[42:43]
	v_cndmask_b32_e64 v156, v183, v165, s[42:43]
	v_pk_mul_f32 v[134:135], v[134:135], v[158:159]
	v_cndmask_b32_e64 v163, v177, v166, s[44:45]
	v_cndmask_b32_e64 v162, v173, v164, s[44:45]
	v_cndmask_b32_e64 v143, v166, v143, s[44:45]
	v_cndmask_b32_e64 v142, v164, v142, s[44:45]
	v_pk_mul_f32 v[136:137], v[136:137], v[156:157]
	v_pk_fma_f32 v[118:119], v[118:119], v[126:127], v[134:135]
	v_cndmask_b32_e64 v161, v184, v172, s[44:45]
	v_cndmask_b32_e64 v160, v181, v169, s[44:45]
	v_pk_fma_f32 v[132:133], v[122:123], v[162:163], v[132:133]
	v_cndmask_b32_e64 v145, v172, v145, s[44:45]
	v_cndmask_b32_e64 v144, v169, v144, s[44:45]
	v_pk_fma_f32 v[120:121], v[120:121], v[128:129], v[136:137]
	v_pk_fma_f32 v[118:119], v[122:123], v[142:143], v[118:119]
	v_pk_fma_f32 v[130:131], v[124:125], v[160:161], v[130:131]
	v_pk_add_f32 v[132:133], v[102:103], v[132:133]
	v_pk_fma_f32 v[120:121], v[124:125], v[144:145], v[120:121]
	v_pk_add_f32 v[102:103], v[102:103], v[118:119]
	v_mov_b32_e32 v118, v198
	v_mov_b32_e32 v119, v198
	v_mov_b32_e32 v199, v198
	v_mov_b32_e32 v201, v200
	v_pk_fma_f32 v[64:65], v[64:65], v[118:119], v[108:109]
	v_mov_b32_e32 v118, v200
	v_mov_b32_e32 v119, v200
	v_mov_b32_dpp v0, v114 row_ror:1 row_mask:0xf bank_mask:0xf
	v_mov_b32_dpp v122, v115 row_ror:1 row_mask:0xf bank_mask:0xf
	v_mov_b32_dpp v123, v116 row_ror:1 row_mask:0xf bank_mask:0xf
	v_mov_b32_dpp v124, v117 row_ror:1 row_mask:0xf bank_mask:0xf
	v_pk_add_f32 v[130:131], v[104:105], v[130:131]
	v_pk_add_f32 v[104:105], v[104:105], v[120:121]
	v_pk_fma_f32 v[62:63], v[62:63], v[198:199], v[106:107]
	v_pk_fma_f32 v[60:61], v[60:61], v[118:119], v[108:109]
	v_pk_fma_f32 v[58:59], v[58:59], v[200:201], v[106:107]
	s_waitcnt lgkmcnt(0)
	v_cndmask_b32_e64 v107, v122, v139, s[42:43]
	v_cndmask_b32_e64 v106, v0, v138, s[42:43]
	v_cndmask_b32_e64 v109, v124, v141, s[42:43]
	v_cndmask_b32_e64 v108, v123, v140, s[42:43]
	v_mov_b32_dpp v120, v114 row_ror:15 row_mask:0xf bank_mask:0xf
	v_mov_b32_dpp v121, v115 row_ror:15 row_mask:0xf bank_mask:0xf
	v_mov_b32_dpp v118, v116 row_ror:15 row_mask:0xf bank_mask:0xf
	v_mov_b32_dpp v119, v117 row_ror:15 row_mask:0xf bank_mask:0xf
	v_mov_b32_dpp v125, v62 row_ror:15 row_mask:0xf bank_mask:0xf
	v_mov_b32_dpp v126, v63 row_ror:15 row_mask:0xf bank_mask:0xf
	v_mov_b32_dpp v127, v64 row_ror:15 row_mask:0xf bank_mask:0xf
	v_mov_b32_dpp v128, v65 row_ror:15 row_mask:0xf bank_mask:0xf
	v_pk_mul_f32 v[108:109], v[96:97], v[108:109]
	v_pk_mul_f32 v[106:107], v[94:95], v[106:107]
	v_cndmask_b32_e64 v119, v119, v128, s[44:45]
	v_cndmask_b32_e64 v118, v118, v127, s[44:45]
	v_cndmask_b32_e64 v121, v121, v126, s[44:45]
	v_cndmask_b32_e64 v120, v120, v125, s[44:45]
	v_pk_fma_f32 v[106:107], v[114:115], v[90:91], v[106:107]
	v_pk_fma_f32 v[108:109], v[116:117], v[92:93], v[108:109]
	v_pk_fma_f32 v[108:109], v[72:73], v[118:119], v[108:109]
	v_pk_fma_f32 v[106:107], v[70:71], v[120:121], v[106:107]
	v_mov_b32_dpp v129, v62 row_ror:1 row_mask:0xf bank_mask:0xf
	v_mov_b32_dpp v134, v63 row_ror:1 row_mask:0xf bank_mask:0xf
	v_mov_b32_dpp v135, v64 row_ror:1 row_mask:0xf bank_mask:0xf
	v_mov_b32_dpp v136, v65 row_ror:1 row_mask:0xf bank_mask:0xf
	v_pk_add_f32 v[114:115], v[68:69], v[108:109]
	v_pk_add_f32 v[116:117], v[66:67], v[106:107]
	v_cndmask_b32_e64 v107, v136, v124, s[42:43]
	v_cndmask_b32_e64 v106, v135, v123, s[42:43]
	v_cndmask_b32_e64 v109, v134, v122, s[42:43]
	v_cndmask_b32_e64 v108, v129, v0, s[42:43]
	v_mov_b32_dpp v137, v58 row_ror:15 row_mask:0xf bank_mask:0xf
	v_mov_b32_dpp v138, v59 row_ror:15 row_mask:0xf bank_mask:0xf
	v_mov_b32_dpp v139, v60 row_ror:15 row_mask:0xf bank_mask:0xf
	v_mov_b32_dpp v140, v61 row_ror:15 row_mask:0xf bank_mask:0xf
	v_pk_mul_f32 v[106:107], v[96:97], v[106:107]
	v_pk_mul_f32 v[108:109], v[94:95], v[108:109]
	v_cndmask_b32_e64 v119, v128, v140, s[44:45]
	v_cndmask_b32_e64 v118, v127, v139, s[44:45]
	v_cndmask_b32_e64 v121, v126, v138, s[44:45]
	v_cndmask_b32_e64 v120, v125, v137, s[44:45]
	v_pk_fma_f32 v[64:65], v[64:65], v[92:93], v[106:107]
	v_pk_fma_f32 v[62:63], v[62:63], v[90:91], v[108:109]
	v_pk_fma_f32 v[64:65], v[72:73], v[118:119], v[64:65]
	v_pk_fma_f32 v[62:63], v[70:71], v[120:121], v[62:63]
	v_mov_b32_dpp v0, v58 row_ror:1 row_mask:0xf bank_mask:0xf
	v_mov_b32_dpp v122, v59 row_ror:1 row_mask:0xf bank_mask:0xf
	v_mov_b32_dpp v123, v60 row_ror:1 row_mask:0xf bank_mask:0xf
	v_mov_b32_dpp v124, v61 row_ror:1 row_mask:0xf bank_mask:0xf
	v_pk_add_f32 v[106:107], v[68:69], v[64:65]
	v_pk_add_f32 v[108:109], v[66:67], v[62:63]
	v_cndmask_b32_e64 v63, v124, v136, s[42:43]
	v_cndmask_b32_e64 v62, v123, v135, s[42:43]
	v_cndmask_b32_e64 v65, v122, v134, s[42:43]
	v_cndmask_b32_e64 v64, v0, v129, s[42:43]
	v_mov_b32_dpp v125, v110 row_ror:15 row_mask:0xf bank_mask:0xf
	v_mov_b32_dpp v126, v111 row_ror:15 row_mask:0xf bank_mask:0xf
	v_mov_b32_dpp v127, v112 row_ror:15 row_mask:0xf bank_mask:0xf
	v_mov_b32_dpp v128, v113 row_ror:15 row_mask:0xf bank_mask:0xf
	v_pk_mul_f32 v[62:63], v[96:97], v[62:63]
	v_pk_mul_f32 v[64:65], v[94:95], v[64:65]
	v_cndmask_b32_e64 v119, v140, v128, s[44:45]
	v_cndmask_b32_e64 v118, v139, v127, s[44:45]
	v_cndmask_b32_e64 v121, v138, v126, s[44:45]
	v_cndmask_b32_e64 v120, v137, v125, s[44:45]
	v_pk_fma_f32 v[60:61], v[60:61], v[92:93], v[62:63]
	v_pk_fma_f32 v[58:59], v[58:59], v[90:91], v[64:65]
	v_pk_fma_f32 v[60:61], v[72:73], v[118:119], v[60:61]
	v_pk_fma_f32 v[58:59], v[70:71], v[120:121], v[58:59]
	v_pk_add_f32 v[62:63], v[68:69], v[60:61]
	v_pk_add_f32 v[64:65], v[66:67], v[58:59]
	v_mov_b32_dpp v60, v110 row_ror:1 row_mask:0xf bank_mask:0xf
	v_mov_b32_dpp v61, v111 row_ror:1 row_mask:0xf bank_mask:0xf
	v_mov_b32_dpp v58, v112 row_ror:1 row_mask:0xf bank_mask:0xf
	v_mov_b32_dpp v59, v113 row_ror:1 row_mask:0xf bank_mask:0xf
	v_cndmask_b32_e64 v59, v59, v124, s[42:43]
	v_cndmask_b32_e64 v58, v58, v123, s[42:43]
	v_cndmask_b32_e64 v61, v61, v122, s[42:43]
	v_cndmask_b32_e64 v60, v60, v0, s[42:43]
	v_pk_mul_f32 v[58:59], v[96:97], v[58:59]
	v_pk_mul_f32 v[60:61], v[94:95], v[60:61]
	v_cndmask_b32_e64 v99, v126, v99, s[44:45]
	v_cndmask_b32_e64 v98, v125, v98, s[44:45]
	v_cndmask_b32_e64 v101, v128, v101, s[44:45]
	v_cndmask_b32_e64 v100, v127, v100, s[44:45]
	v_pk_fma_f32 v[58:59], v[112:113], v[92:93], v[58:59]
	v_pk_fma_f32 v[60:61], v[110:111], v[90:91], v[60:61]
	v_pk_fma_f32 v[58:59], v[72:73], v[100:101], v[58:59]
	v_pk_fma_f32 v[60:61], v[70:71], v[98:99], v[60:61]
	v_pk_add_f32 v[58:59], v[68:69], v[58:59]
	v_pk_add_f32 v[60:61], v[66:67], v[60:61]
	v_mul_f32_e32 v0, 0xbfb8aa3b, v154
	v_mul_f32_e32 v66, 0xbfb8aa3b, v155
	v_exp_f32_e32 v0, v0
	v_exp_f32_e32 v66, v66
	v_mul_f32_e32 v67, 0xbfb8aa3b, v152
	v_exp_f32_e32 v67, v67
	v_mul_f32_e32 v68, 0xbfb8aa3b, v153
	v_exp_f32_e32 v68, v68
	v_add_f32_e32 v0, 1.0, v0
	v_add_f32_e32 v66, 1.0, v66
	v_rcp_f32_e32 v0, v0
	v_rcp_f32_e32 v66, v66
	v_add_f32_e32 v67, 1.0, v67
	v_rcp_f32_e32 v67, v67
	v_add_f32_e32 v68, 1.0, v68
	v_rcp_f32_e32 v68, v68
	v_mul_f32_e32 v0, v154, v0
	v_mul_f32_e32 v66, v155, v66
	v_mul_f32_e32 v0, v0, v116
	v_mul_f32_e32 v66, v66, v117
	v_mul_f32_e32 v67, v152, v67
	v_mul_f32_e32 v67, v67, v114
	v_mul_f32_e32 v68, v153, v68
	v_cvt_pk_bf16_f32 v66, v0, v66
	v_mov_b32_e32 v0, v150
	v_mul_f32_e32 v68, v68, v115
	v_cvt_pk_bf16_f32 v67, v67, v68
	s_nop 0
	v_add_u32_e32 v0, 0x58000, v0
	v_lshl_add_u64 v[68:69], v[0:1], 1, s[62:63]
	global_store_dwordx2 v[68:69], v[66:67], off
	v_mul_f32_e32 v0, 0xbfb8aa3b, v148
	v_mul_f32_e32 v66, 0xbfb8aa3b, v149
	v_exp_f32_e32 v0, v0
	v_exp_f32_e32 v66, v66
	v_mul_f32_e32 v67, 0xbfb8aa3b, v146
	v_exp_f32_e32 v67, v67
	v_mul_f32_e32 v68, 0xbfb8aa3b, v147
	v_exp_f32_e32 v68, v68
	v_add_f32_e32 v0, 1.0, v0
	v_add_f32_e32 v66, 1.0, v66
	v_rcp_f32_e32 v0, v0
	v_rcp_f32_e32 v66, v66
	v_add_f32_e32 v67, 1.0, v67
	v_rcp_f32_e32 v67, v67
	v_add_f32_e32 v68, 1.0, v68
	v_rcp_f32_e32 v68, v68
	v_mul_f32_e32 v0, v148, v0
	v_mul_f32_e32 v66, v149, v66
	v_mul_f32_e32 v0, v0, v108
	v_mul_f32_e32 v66, v66, v109
	v_mul_f32_e32 v67, v146, v67
	v_mul_f32_e32 v67, v67, v106
	v_mul_f32_e32 v68, v147, v68
	v_cvt_pk_bf16_f32 v66, v0, v66
	v_mov_b32_e32 v0, v150
	v_mul_f32_e32 v68, v68, v107
	v_cvt_pk_bf16_f32 v67, v67, v68
	s_nop 0
	v_add_u32_e32 v0, 0x63000, v0
	v_lshl_add_u64 v[68:69], v[0:1], 1, s[62:63]
	v_mul_f32_e32 v0, 0xbfb8aa3b, v132
	v_exp_f32_e32 v0, v0
	global_store_dwordx2 v[68:69], v[66:67], off
	v_add_f32_e32 v0, 1.0, v0
	v_rcp_f32_e32 v0, v0
	s_nop 0
	v_mul_f32_e32 v0, v132, v0
	v_mul_f32_e32 v0, v0, v64
	v_mul_f32_e32 v64, 0xbfb8aa3b, v133
	v_exp_f32_e32 v64, v64
	s_nop 0
	v_add_f32_e32 v64, 1.0, v64
	v_rcp_f32_e32 v64, v64
	s_nop 0
	v_mul_f32_e32 v64, v133, v64
	v_mul_f32_e32 v64, v64, v65
	v_mul_f32_e32 v65, 0xbfb8aa3b, v130
	v_exp_f32_e32 v65, v65
	s_nop 0
	v_add_f32_e32 v65, 1.0, v65
	v_rcp_f32_e32 v65, v65
	s_nop 0
	v_mul_f32_e32 v65, v130, v65
	v_mul_f32_e32 v65, v65, v62
	v_mul_f32_e32 v62, 0xbfb8aa3b, v131
	v_exp_f32_e32 v62, v62
	s_nop 0
	v_add_f32_e32 v62, 1.0, v62
	v_rcp_f32_e32 v62, v62
	s_nop 0
	v_mul_f32_e32 v62, v131, v62
	v_mul_f32_e32 v63, v62, v63
	v_cvt_pk_bf16_f32 v62, v0, v64
	v_mov_b32_e32 v0, v150
	v_cvt_pk_bf16_f32 v63, v65, v63
	s_nop 0
	v_add_u32_e32 v0, 0x6e000, v0
	v_lshl_add_u64 v[64:65], v[0:1], 1, s[62:63]
	v_mul_f32_e32 v0, 0xbfb8aa3b, v102
	v_exp_f32_e32 v0, v0
	global_store_dwordx2 v[64:65], v[62:63], off
	v_add_f32_e32 v0, 1.0, v0
	v_rcp_f32_e32 v0, v0
	s_nop 0
	v_mul_f32_e32 v0, v102, v0
	v_mul_f32_e32 v0, v0, v60
	v_mul_f32_e32 v60, 0xbfb8aa3b, v103
	v_exp_f32_e32 v60, v60
	s_nop 0
	v_add_f32_e32 v60, 1.0, v60
	v_rcp_f32_e32 v60, v60
	s_nop 0
	v_mul_f32_e32 v60, v103, v60
	v_mul_f32_e32 v60, v60, v61
	v_mul_f32_e32 v61, 0xbfb8aa3b, v104
	v_exp_f32_e32 v61, v61
	s_nop 0
	v_add_f32_e32 v61, 1.0, v61
	v_rcp_f32_e32 v61, v61
	s_nop 0
	v_mul_f32_e32 v61, v104, v61
	v_mul_f32_e32 v61, v61, v58
	v_mul_f32_e32 v58, 0xbfb8aa3b, v105
	v_exp_f32_e32 v58, v58
	s_nop 0
	v_add_f32_e32 v58, 1.0, v58
	v_rcp_f32_e32 v58, v58
	s_nop 0
	v_mul_f32_e32 v58, v105, v58
	v_mul_f32_e32 v59, v58, v59
	v_cvt_pk_bf16_f32 v58, v0, v60
	v_mov_b32_e32 v0, v150
	v_cvt_pk_bf16_f32 v59, v61, v59
	s_nop 0
	v_add_u32_e32 v0, 0x79000, v0
	v_lshl_add_u64 v[60:61], v[0:1], 1, s[62:63]
	global_store_dwordx2 v[60:61], v[58:59], off
	ds_read_b128 v[98:101], v209 offset:16
	ds_read_b128 v[94:97], v209 offset:528
	ds_read_b128 v[90:93], v209 offset:1040
	ds_read_b128 v[70:73], v209 offset:1552
	v_mov_b32_e32 v102, 0
	s_and_b64 vcc, exec, s[46:47]
	v_mov_b32_e32 v110, 0
	v_mov_b32_e32 v111, 0
	v_mov_b32_e32 v112, 0
	v_mov_b32_e32 v113, 0
	s_cbranch_vccnz .LBB0_391
	v_add_u32_e32 v0, 0xfffffc10, v240
	ds_read_b128 v[110:113], v0

.LBB0_393:
	v_mov_b32_e32 v58, v202
	v_mov_b32_e32 v59, v202
	v_pk_fma_f32 v[124:125], v[30:31], v[202:203], v[54:55]
	v_mov_b32_e32 v30, v204
	v_mov_b32_e32 v31, v204
	v_pk_fma_f32 v[122:123], v[32:33], v[58:59], v[56:57]
	v_pk_fma_f32 v[118:119], v[28:29], v[30:31], v[56:57]
	v_pk_fma_f32 v[120:121], v[26:27], v[204:205], v[54:55]
	v_mov_b32_dpp v133, v86 row_ror:1 row_mask:0xf bank_mask:0xf
	v_mov_b32_dpp v137, v87 row_ror:1 row_mask:0xf bank_mask:0xf
	v_mov_b32_dpp v141, v88 row_ror:1 row_mask:0xf bank_mask:0xf
	v_mov_b32_dpp v145, v89 row_ror:1 row_mask:0xf bank_mask:0xf
	v_mov_b32_dpp v114, v86 row_ror:15 row_mask:0xf bank_mask:0xf
	v_mov_b32_dpp v115, v87 row_ror:15 row_mask:0xf bank_mask:0xf
	v_mov_b32_dpp v116, v88 row_ror:15 row_mask:0xf bank_mask:0xf
	v_mov_b32_dpp v117, v89 row_ror:15 row_mask:0xf bank_mask:0xf
	v_mov_b32_dpp v148, v124 row_ror:15 row_mask:0xf bank_mask:0xf
	v_mov_b32_dpp v151, v125 row_ror:15 row_mask:0xf bank_mask:0xf
	v_mov_b32_dpp v152, v122 row_ror:15 row_mask:0xf bank_mask:0xf
	v_mov_b32_dpp v153, v123 row_ror:15 row_mask:0xf bank_mask:0xf
	v_mov_b32_dpp v131, v124 row_ror:1 row_mask:0xf bank_mask:0xf
	v_mov_b32_dpp v134, v125 row_ror:1 row_mask:0xf bank_mask:0xf
	v_mov_b32_dpp v138, v122 row_ror:1 row_mask:0xf bank_mask:0xf
	v_mov_b32_dpp v142, v123 row_ror:1 row_mask:0xf bank_mask:0xf
	v_mov_b32_dpp v136, v120 row_ror:15 row_mask:0xf bank_mask:0xf
	v_mov_b32_dpp v140, v121 row_ror:15 row_mask:0xf bank_mask:0xf
	v_mov_b32_dpp v144, v118 row_ror:15 row_mask:0xf bank_mask:0xf
	v_mov_b32_dpp v147, v119 row_ror:15 row_mask:0xf bank_mask:0xf
	v_mov_b32_dpp v0, v120 row_ror:1 row_mask:0xf bank_mask:0xf
	v_mov_b32_dpp v126, v121 row_ror:1 row_mask:0xf bank_mask:0xf
	v_mov_b32_dpp v128, v118 row_ror:1 row_mask:0xf bank_mask:0xf
	v_mov_b32_dpp v130, v119 row_ror:1 row_mask:0xf bank_mask:0xf
	v_mov_b32_dpp v127, v82 row_ror:15 row_mask:0xf bank_mask:0xf
	v_mov_b32_dpp v129, v83 row_ror:15 row_mask:0xf bank_mask:0xf
	v_mov_b32_dpp v132, v84 row_ror:15 row_mask:0xf bank_mask:0xf
	v_mov_b32_dpp v135, v85 row_ror:15 row_mask:0xf bank_mask:0xf
	v_mov_b32_dpp v139, v82 row_ror:1 row_mask:0xf bank_mask:0xf
	v_mov_b32_dpp v143, v83 row_ror:1 row_mask:0xf bank_mask:0xf
	v_mov_b32_dpp v146, v84 row_ror:1 row_mask:0xf bank_mask:0xf
	v_mov_b32_dpp v149, v85 row_ror:1 row_mask:0xf bank_mask:0xf
	ds_read_b128 v[62:65], v209 offset:2064
	ds_read_b128 v[58:61], v209 offset:2576
	ds_read_b128 v[30:33], v209 offset:3088
	ds_read_b128 v[26:29], v209 offset:3600
	v_mov_b32_e32 v66, 0
	s_and_b64 vcc, exec, s[46:47]
	v_mov_b32_e32 v106, 0
	v_mov_b32_e32 v107, 0
	v_mov_b32_e32 v108, 0
	v_mov_b32_e32 v109, 0
	s_cbranch_vccnz .LBB0_395
	v_add_u32_e32 v67, 0xfffffe10, v240
	ds_read_b128 v[106:109], v67

.LBB0_397:
	s_waitcnt lgkmcnt(4)
	v_cndmask_b32_e64 v113, v145, v113, s[42:43]
	v_cndmask_b32_e64 v112, v141, v112, s[42:43]
	v_cndmask_b32_e64 v111, v137, v111, s[42:43]
	v_cndmask_b32_e64 v110, v133, v110, s[42:43]
	v_pk_mul_f32 v[112:113], v[100:101], v[112:113]
	v_cndmask_b32_e64 v117, v117, v153, s[44:45]
	v_cndmask_b32_e64 v116, v116, v152, s[44:45]
	v_pk_mul_f32 v[110:111], v[98:99], v[110:111]
	v_pk_fma_f32 v[88:89], v[88:89], v[96:97], v[112:113]
	v_cndmask_b32_e64 v115, v115, v151, s[44:45]
	v_cndmask_b32_e64 v114, v114, v148, s[44:45]
	v_pk_fma_f32 v[86:87], v[86:87], v[94:95], v[110:111]
	v_pk_fma_f32 v[88:89], v[92:93], v[116:117], v[88:89]
	v_pk_fma_f32 v[86:87], v[90:91], v[114:115], v[86:87]
	v_pk_add_f32 v[114:115], v[72:73], v[88:89]
	v_cndmask_b32_e64 v89, v134, v137, s[42:43]
	v_cndmask_b32_e64 v88, v131, v133, s[42:43]
	v_pk_mul_f32 v[88:89], v[98:99], v[88:89]
	v_pk_add_f32 v[116:117], v[70:71], v[86:87]
	v_cndmask_b32_e64 v87, v142, v145, s[42:43]
	v_cndmask_b32_e64 v86, v138, v141, s[42:43]
	v_cndmask_b32_e64 v113, v151, v140, s[44:45]
	v_cndmask_b32_e64 v112, v148, v136, s[44:45]
	v_pk_fma_f32 v[88:89], v[124:125], v[94:95], v[88:89]
	v_pk_mul_f32 v[86:87], v[100:101], v[86:87]
	v_pk_fma_f32 v[88:89], v[90:91], v[112:113], v[88:89]
	v_cndmask_b32_e64 v111, v153, v147, s[44:45]
	v_cndmask_b32_e64 v110, v152, v144, s[44:45]
	v_pk_fma_f32 v[86:87], v[122:123], v[96:97], v[86:87]
	v_pk_add_f32 v[112:113], v[70:71], v[88:89]
	v_cndmask_b32_e64 v89, v126, v134, s[42:43]
	v_cndmask_b32_e64 v88, v0, v131, s[42:43]
	v_pk_fma_f32 v[86:87], v[92:93], v[110:111], v[86:87]
	v_pk_mul_f32 v[88:89], v[98:99], v[88:89]
	v_pk_add_f32 v[110:111], v[72:73], v[86:87]
	v_cndmask_b32_e64 v87, v130, v142, s[42:43]
	v_cndmask_b32_e64 v86, v128, v138, s[42:43]
	v_pk_fma_f32 v[88:89], v[120:121], v[94:95], v[88:89]
	v_cndmask_b32_e64 v121, v143, v126, s[42:43]
	v_cndmask_b32_e64 v120, v139, v0, s[42:43]
	v_pk_mul_f32 v[86:87], v[100:101], v[86:87]
	v_pk_mul_f32 v[98:99], v[98:99], v[120:121]
	v_cndmask_b32_e64 v125, v140, v129, s[44:45]
	v_cndmask_b32_e64 v124, v136, v127, s[44:45]
	v_pk_fma_f32 v[86:87], v[118:119], v[96:97], v[86:87]
	v_cndmask_b32_e64 v119, v149, v130, s[42:43]
	v_cndmask_b32_e64 v118, v146, v128, s[42:43]
	v_cndmask_b32_e64 v103, v129, v103, s[44:45]
	v_cndmask_b32_e64 v102, v127, v102, s[44:45]
	v_pk_fma_f32 v[82:83], v[82:83], v[94:95], v[98:99]
	v_pk_fma_f32 v[88:89], v[90:91], v[124:125], v[88:89]
	v_pk_mul_f32 v[100:101], v[100:101], v[118:119]
	v_pk_fma_f32 v[82:83], v[90:91], v[102:103], v[82:83]
	v_cndmask_b32_e64 v123, v147, v135, s[44:45]
	v_cndmask_b32_e64 v122, v144, v132, s[44:45]
	v_pk_add_f32 v[88:89], v[70:71], v[88:89]
	v_cndmask_b32_e64 v105, v135, v105, s[44:45]
	v_cndmask_b32_e64 v104, v132, v104, s[44:45]
	v_pk_fma_f32 v[84:85], v[84:85], v[96:97], v[100:101]
	v_pk_add_f32 v[70:71], v[70:71], v[82:83]
	v_mov_b32_e32 v82, v202
	v_mov_b32_e32 v83, v202
	v_pk_fma_f32 v[86:87], v[92:93], v[122:123], v[86:87]
	v_pk_fma_f32 v[84:85], v[92:93], v[104:105], v[84:85]
	v_pk_fma_f32 v[24:25], v[24:25], v[82:83], v[36:37]
	v_mov_b32_e32 v82, v204
	v_mov_b32_e32 v83, v204
	v_mov_b32_dpp v0, v78 row_ror:1 row_mask:0xf bank_mask:0xf
	v_mov_b32_dpp v94, v79 row_ror:1 row_mask:0xf bank_mask:0xf
	v_mov_b32_dpp v95, v80 row_ror:1 row_mask:0xf bank_mask:0xf
	v_mov_b32_dpp v96, v81 row_ror:1 row_mask:0xf bank_mask:0xf
	v_pk_add_f32 v[86:87], v[72:73], v[86:87]
	v_pk_add_f32 v[72:73], v[72:73], v[84:85]
	v_pk_fma_f32 v[22:23], v[22:23], v[202:203], v[34:35]
	v_pk_fma_f32 v[20:21], v[20:21], v[82:83], v[36:37]
	s_waitcnt lgkmcnt(0)
	v_cndmask_b32_e64 v83, v94, v107, s[42:43]
	v_cndmask_b32_e64 v82, v0, v106, s[42:43]
	v_cndmask_b32_e64 v85, v96, v109, s[42:43]
	v_cndmask_b32_e64 v84, v95, v108, s[42:43]
	v_mov_b32_dpp v92, v78 row_ror:15 row_mask:0xf bank_mask:0xf
	v_mov_b32_dpp v93, v79 row_ror:15 row_mask:0xf bank_mask:0xf
	v_mov_b32_dpp v90, v80 row_ror:15 row_mask:0xf bank_mask:0xf
	v_mov_b32_dpp v91, v81 row_ror:15 row_mask:0xf bank_mask:0xf
	v_mov_b32_dpp v97, v22 row_ror:15 row_mask:0xf bank_mask:0xf
	v_mov_b32_dpp v98, v23 row_ror:15 row_mask:0xf bank_mask:0xf
	v_mov_b32_dpp v99, v24 row_ror:15 row_mask:0xf bank_mask:0xf
	v_mov_b32_dpp v100, v25 row_ror:15 row_mask:0xf bank_mask:0xf
	v_pk_mul_f32 v[84:85], v[64:65], v[84:85]
	v_pk_mul_f32 v[82:83], v[62:63], v[82:83]
	v_cndmask_b32_e64 v91, v91, v100, s[44:45]
	v_cndmask_b32_e64 v90, v90, v99, s[44:45]
	v_cndmask_b32_e64 v93, v93, v98, s[44:45]
	v_cndmask_b32_e64 v92, v92, v97, s[44:45]
	v_pk_fma_f32 v[78:79], v[78:79], v[58:59], v[82:83]
	v_pk_fma_f32 v[80:81], v[80:81], v[60:61], v[84:85]
	v_pk_fma_f32 v[80:81], v[32:33], v[90:91], v[80:81]
	v_pk_fma_f32 v[78:79], v[30:31], v[92:93], v[78:79]
	v_mov_b32_dpp v101, v22 row_ror:1 row_mask:0xf bank_mask:0xf
	v_mov_b32_dpp v102, v23 row_ror:1 row_mask:0xf bank_mask:0xf
	v_mov_b32_dpp v103, v24 row_ror:1 row_mask:0xf bank_mask:0xf
	v_mov_b32_dpp v104, v25 row_ror:1 row_mask:0xf bank_mask:0xf
	v_pk_fma_f32 v[18:19], v[18:19], v[204:205], v[34:35]
	v_pk_add_f32 v[82:83], v[28:29], v[80:81]
	v_pk_add_f32 v[84:85], v[26:27], v[78:79]
	v_cndmask_b32_e64 v79, v104, v96, s[42:43]
	v_cndmask_b32_e64 v78, v103, v95, s[42:43]
	v_cndmask_b32_e64 v81, v102, v94, s[42:43]
	v_cndmask_b32_e64 v80, v101, v0, s[42:43]
	v_mov_b32_dpp v105, v18 row_ror:15 row_mask:0xf bank_mask:0xf
	v_mov_b32_dpp v106, v19 row_ror:15 row_mask:0xf bank_mask:0xf
	v_mov_b32_dpp v107, v20 row_ror:15 row_mask:0xf bank_mask:0xf
	v_mov_b32_dpp v108, v21 row_ror:15 row_mask:0xf bank_mask:0xf
	v_pk_mul_f32 v[78:79], v[64:65], v[78:79]
	v_pk_mul_f32 v[80:81], v[62:63], v[80:81]
	v_cndmask_b32_e64 v91, v100, v108, s[44:45]
	v_cndmask_b32_e64 v90, v99, v107, s[44:45]
	v_cndmask_b32_e64 v93, v98, v106, s[44:45]
	v_cndmask_b32_e64 v92, v97, v105, s[44:45]
	v_pk_fma_f32 v[24:25], v[24:25], v[60:61], v[78:79]
	v_pk_fma_f32 v[22:23], v[22:23], v[58:59], v[80:81]
	v_pk_fma_f32 v[24:25], v[32:33], v[90:91], v[24:25]
	v_pk_fma_f32 v[22:23], v[30:31], v[92:93], v[22:23]
	v_mov_b32_dpp v0, v18 row_ror:1 row_mask:0xf bank_mask:0xf
	v_mov_b32_dpp v94, v19 row_ror:1 row_mask:0xf bank_mask:0xf
	v_mov_b32_dpp v95, v20 row_ror:1 row_mask:0xf bank_mask:0xf
	v_mov_b32_dpp v96, v21 row_ror:1 row_mask:0xf bank_mask:0xf
	v_pk_add_f32 v[78:79], v[28:29], v[24:25]
	v_pk_add_f32 v[80:81], v[26:27], v[22:23]
	v_cndmask_b32_e64 v23, v96, v104, s[42:43]
	v_cndmask_b32_e64 v22, v95, v103, s[42:43]
	v_cndmask_b32_e64 v25, v94, v102, s[42:43]
	v_cndmask_b32_e64 v24, v0, v101, s[42:43]
	v_mov_b32_dpp v97, v74 row_ror:15 row_mask:0xf bank_mask:0xf
	v_mov_b32_dpp v98, v75 row_ror:15 row_mask:0xf bank_mask:0xf
	v_mov_b32_dpp v99, v76 row_ror:15 row_mask:0xf bank_mask:0xf
	v_mov_b32_dpp v100, v77 row_ror:15 row_mask:0xf bank_mask:0xf
	v_pk_mul_f32 v[22:23], v[64:65], v[22:23]
	v_pk_mul_f32 v[24:25], v[62:63], v[24:25]
	v_cndmask_b32_e64 v91, v108, v100, s[44:45]
	v_cndmask_b32_e64 v90, v107, v99, s[44:45]
	v_cndmask_b32_e64 v93, v106, v98, s[44:45]
	v_cndmask_b32_e64 v92, v105, v97, s[44:45]
	v_pk_fma_f32 v[20:21], v[20:21], v[60:61], v[22:23]
	v_pk_fma_f32 v[18:19], v[18:19], v[58:59], v[24:25]
	v_pk_fma_f32 v[20:21], v[32:33], v[90:91], v[20:21]
	v_pk_fma_f32 v[18:19], v[30:31], v[92:93], v[18:19]
	v_pk_add_f32 v[22:23], v[28:29], v[20:21]
	v_pk_add_f32 v[24:25], v[26:27], v[18:19]
	v_mov_b32_dpp v20, v74 row_ror:1 row_mask:0xf bank_mask:0xf
	v_mov_b32_dpp v21, v75 row_ror:1 row_mask:0xf bank_mask:0xf
	v_mov_b32_dpp v18, v76 row_ror:1 row_mask:0xf bank_mask:0xf
	v_mov_b32_dpp v19, v77 row_ror:1 row_mask:0xf bank_mask:0xf
	v_cndmask_b32_e64 v19, v19, v96, s[42:43]
	v_cndmask_b32_e64 v18, v18, v95, s[42:43]
	v_cndmask_b32_e64 v21, v21, v94, s[42:43]
	v_cndmask_b32_e64 v20, v20, v0, s[42:43]
	v_pk_mul_f32 v[18:19], v[64:65], v[18:19]
	v_pk_mul_f32 v[20:21], v[62:63], v[20:21]
	v_cndmask_b32_e64 v67, v98, v67, s[44:45]
	v_cndmask_b32_e64 v66, v97, v66, s[44:45]
	v_cndmask_b32_e64 v69, v100, v69, s[44:45]
	v_cndmask_b32_e64 v68, v99, v68, s[44:45]
	v_pk_fma_f32 v[18:19], v[76:77], v[60:61], v[18:19]
	v_pk_fma_f32 v[20:21], v[74:75], v[58:59], v[20:21]
	v_pk_fma_f32 v[18:19], v[32:33], v[68:69], v[18:19]
	v_pk_fma_f32 v[20:21], v[30:31], v[66:67], v[20:21]
	v_pk_add_f32 v[18:19], v[28:29], v[18:19]
	v_pk_add_f32 v[20:21], v[26:27], v[20:21]
	v_mul_f32_e32 v0, 0xbfb8aa3b, v116
	v_mul_f32_e32 v26, 0xbfb8aa3b, v117
	v_exp_f32_e32 v0, v0
	v_exp_f32_e32 v26, v26
	v_mul_f32_e32 v27, 0xbfb8aa3b, v114
	v_exp_f32_e32 v27, v27
	v_mul_f32_e32 v28, 0xbfb8aa3b, v115
	v_exp_f32_e32 v28, v28
	v_add_f32_e32 v0, 1.0, v0
	v_add_f32_e32 v26, 1.0, v26
	v_rcp_f32_e32 v0, v0
	v_rcp_f32_e32 v26, v26
	v_add_f32_e32 v27, 1.0, v27
	v_rcp_f32_e32 v27, v27
	v_add_f32_e32 v28, 1.0, v28
	v_rcp_f32_e32 v28, v28
	v_mul_f32_e32 v0, v116, v0
	v_mul_f32_e32 v26, v117, v26
	v_mul_f32_e32 v0, v0, v84
	v_mul_f32_e32 v26, v26, v85
	v_mul_f32_e32 v27, v114, v27
	v_mul_f32_e32 v27, v27, v82
	v_mul_f32_e32 v28, v115, v28
	v_cvt_pk_bf16_f32 v26, v0, v26
	v_mov_b32_e32 v0, v150
	v_mul_f32_e32 v28, v28, v83
	v_cvt_pk_bf16_f32 v27, v27, v28
	s_nop 0
	v_add_u32_e32 v0, 4, v0
	v_lshl_add_u64 v[28:29], v[0:1], 1, s[62:63]
	global_store_dwordx2 v[28:29], v[26:27], off
	v_mul_f32_e32 v0, 0xbfb8aa3b, v112
	v_mul_f32_e32 v26, 0xbfb8aa3b, v113
	v_exp_f32_e32 v0, v0
	v_exp_f32_e32 v26, v26
	v_mul_f32_e32 v27, 0xbfb8aa3b, v110
	v_exp_f32_e32 v27, v27
	v_mul_f32_e32 v28, 0xbfb8aa3b, v111
	v_exp_f32_e32 v28, v28
	v_add_f32_e32 v0, 1.0, v0
	v_add_f32_e32 v26, 1.0, v26
	v_rcp_f32_e32 v0, v0
	v_rcp_f32_e32 v26, v26
	v_add_f32_e32 v27, 1.0, v27
	v_rcp_f32_e32 v27, v27
	v_add_f32_e32 v28, 1.0, v28
	v_rcp_f32_e32 v28, v28
	v_mul_f32_e32 v0, v112, v0
	v_mul_f32_e32 v26, v113, v26
	v_mul_f32_e32 v0, v0, v80
	v_mul_f32_e32 v26, v26, v81
	v_mul_f32_e32 v27, v110, v27
	v_mul_f32_e32 v27, v27, v78
	v_mul_f32_e32 v28, v111, v28
	v_cvt_pk_bf16_f32 v26, v0, v26
	v_mov_b32_e32 v0, v150
	v_mul_f32_e32 v28, v28, v79
	v_cvt_pk_bf16_f32 v27, v27, v28
	s_nop 0
	v_add_u32_e32 v0, 0xb004, v0
	v_lshl_add_u64 v[28:29], v[0:1], 1, s[62:63]
	v_mul_f32_e32 v0, 0xbfb8aa3b, v88
	v_exp_f32_e32 v0, v0
	global_store_dwordx2 v[28:29], v[26:27], off
	v_add_f32_e32 v0, 1.0, v0
	v_rcp_f32_e32 v0, v0
	s_nop 0
	v_mul_f32_e32 v0, v88, v0
	v_mul_f32_e32 v0, v0, v24
	v_mul_f32_e32 v24, 0xbfb8aa3b, v89
	v_exp_f32_e32 v24, v24
	s_nop 0
	v_add_f32_e32 v24, 1.0, v24
	v_rcp_f32_e32 v24, v24
	s_nop 0
	v_mul_f32_e32 v24, v89, v24
	v_mul_f32_e32 v24, v24, v25
	v_mul_f32_e32 v25, 0xbfb8aa3b, v86
	v_exp_f32_e32 v25, v25
	s_nop 0
	v_add_f32_e32 v25, 1.0, v25
	v_rcp_f32_e32 v25, v25
	s_nop 0
	v_mul_f32_e32 v25, v86, v25
	v_mul_f32_e32 v25, v25, v22
	v_mul_f32_e32 v22, 0xbfb8aa3b, v87
	v_exp_f32_e32 v22, v22
	s_nop 0
	v_add_f32_e32 v22, 1.0, v22
	v_rcp_f32_e32 v22, v22
	s_nop 0
	v_mul_f32_e32 v22, v87, v22
	v_mul_f32_e32 v23, v22, v23
	v_cvt_pk_bf16_f32 v22, v0, v24
	v_mov_b32_e32 v0, v150
	v_cvt_pk_bf16_f32 v23, v25, v23
	s_nop 0
	v_add_u32_e32 v0, 0x16004, v0
	v_lshl_add_u64 v[24:25], v[0:1], 1, s[62:63]
	v_mul_f32_e32 v0, 0xbfb8aa3b, v70
	v_exp_f32_e32 v0, v0
	global_store_dwordx2 v[24:25], v[22:23], off
	v_add_f32_e32 v0, 1.0, v0
	v_rcp_f32_e32 v0, v0
	s_nop 0
	v_mul_f32_e32 v0, v70, v0
	v_mul_f32_e32 v0, v0, v20
	v_mul_f32_e32 v20, 0xbfb8aa3b, v71
	v_exp_f32_e32 v20, v20
	s_nop 0
	v_add_f32_e32 v20, 1.0, v20
	v_rcp_f32_e32 v20, v20
	s_nop 0
	v_mul_f32_e32 v20, v71, v20
	v_mul_f32_e32 v20, v20, v21
	v_mul_f32_e32 v21, 0xbfb8aa3b, v72
	v_exp_f32_e32 v21, v21
	s_nop 0
	v_add_f32_e32 v21, 1.0, v21
	v_rcp_f32_e32 v21, v21
	s_nop 0
	v_mul_f32_e32 v21, v72, v21
	v_mul_f32_e32 v21, v21, v18
	v_mul_f32_e32 v18, 0xbfb8aa3b, v73
	v_exp_f32_e32 v18, v18
	s_nop 0
	v_add_f32_e32 v18, 1.0, v18
	v_rcp_f32_e32 v18, v18
	s_nop 0
	v_mul_f32_e32 v18, v73, v18
	v_mul_f32_e32 v19, v18, v19
	v_cvt_pk_bf16_f32 v18, v0, v20
	v_mov_b32_e32 v0, v150
	v_cvt_pk_bf16_f32 v19, v21, v19
	s_nop 0
	v_add_u32_e32 v0, 0x21004, v0
	v_lshl_add_u64 v[20:21], v[0:1], 1, s[62:63]
	global_store_dwordx2 v[20:21], v[18:19], off
	ds_read_b128 v[66:69], v209 offset:16
	ds_read_b128 v[62:65], v209 offset:528
	ds_read_b128 v[58:61], v209 offset:1040
	ds_read_b128 v[30:33], v209 offset:1552
	v_mov_b32_e32 v70, 0
	s_and_b64 vcc, exec, s[50:51]
	v_mov_b32_e32 v74, 0
	v_mov_b32_e32 v75, 0
	v_mov_b32_e32 v76, 0
	v_mov_b32_e32 v77, 0
	s_cbranch_vccnz .LBB0_399
	ds_read_b128 v[74:77], v240 offset:3088

.LBB0_401:
	v_mov_b32_e32 v18, v198
	v_mov_b32_e32 v19, v198
	v_pk_fma_f32 v[88:89], v[14:15], v[198:199], v[54:55]
	v_mov_b32_e32 v14, v200
	v_mov_b32_e32 v15, v200
	v_pk_fma_f32 v[86:87], v[16:17], v[18:19], v[56:57]
	v_pk_fma_f32 v[82:83], v[12:13], v[14:15], v[56:57]
	v_pk_fma_f32 v[84:85], v[10:11], v[200:201], v[54:55]
	v_mov_b32_dpp v97, v50 row_ror:1 row_mask:0xf bank_mask:0xf
	v_mov_b32_dpp v101, v51 row_ror:1 row_mask:0xf bank_mask:0xf
	v_mov_b32_dpp v105, v52 row_ror:1 row_mask:0xf bank_mask:0xf
	v_mov_b32_dpp v109, v53 row_ror:1 row_mask:0xf bank_mask:0xf
	v_mov_b32_dpp v78, v50 row_ror:15 row_mask:0xf bank_mask:0xf
	v_mov_b32_dpp v79, v51 row_ror:15 row_mask:0xf bank_mask:0xf
	v_mov_b32_dpp v80, v52 row_ror:15 row_mask:0xf bank_mask:0xf
	v_mov_b32_dpp v81, v53 row_ror:15 row_mask:0xf bank_mask:0xf
	v_mov_b32_dpp v112, v88 row_ror:15 row_mask:0xf bank_mask:0xf
	v_mov_b32_dpp v114, v89 row_ror:15 row_mask:0xf bank_mask:0xf
	v_mov_b32_dpp v115, v86 row_ror:15 row_mask:0xf bank_mask:0xf
	v_mov_b32_dpp v116, v87 row_ror:15 row_mask:0xf bank_mask:0xf
	v_mov_b32_dpp v95, v88 row_ror:1 row_mask:0xf bank_mask:0xf
	v_mov_b32_dpp v98, v89 row_ror:1 row_mask:0xf bank_mask:0xf
	v_mov_b32_dpp v102, v86 row_ror:1 row_mask:0xf bank_mask:0xf
	v_mov_b32_dpp v106, v87 row_ror:1 row_mask:0xf bank_mask:0xf
	v_mov_b32_dpp v100, v84 row_ror:15 row_mask:0xf bank_mask:0xf
	v_mov_b32_dpp v104, v85 row_ror:15 row_mask:0xf bank_mask:0xf
	v_mov_b32_dpp v108, v82 row_ror:15 row_mask:0xf bank_mask:0xf
	v_mov_b32_dpp v111, v83 row_ror:15 row_mask:0xf bank_mask:0xf
	v_mov_b32_dpp v0, v84 row_ror:1 row_mask:0xf bank_mask:0xf
	v_mov_b32_dpp v90, v85 row_ror:1 row_mask:0xf bank_mask:0xf
	v_mov_b32_dpp v92, v82 row_ror:1 row_mask:0xf bank_mask:0xf
	v_mov_b32_dpp v94, v83 row_ror:1 row_mask:0xf bank_mask:0xf
	v_mov_b32_dpp v91, v46 row_ror:15 row_mask:0xf bank_mask:0xf
	v_mov_b32_dpp v93, v47 row_ror:15 row_mask:0xf bank_mask:0xf
	v_mov_b32_dpp v96, v48 row_ror:15 row_mask:0xf bank_mask:0xf
	v_mov_b32_dpp v99, v49 row_ror:15 row_mask:0xf bank_mask:0xf
	v_mov_b32_dpp v103, v46 row_ror:1 row_mask:0xf bank_mask:0xf
	v_mov_b32_dpp v107, v47 row_ror:1 row_mask:0xf bank_mask:0xf
	v_mov_b32_dpp v110, v48 row_ror:1 row_mask:0xf bank_mask:0xf
	v_mov_b32_dpp v113, v49 row_ror:1 row_mask:0xf bank_mask:0xf
	ds_read_b128 v[22:25], v209 offset:2064
	ds_read_b128 v[18:21], v209 offset:2576
	ds_read_b128 v[14:17], v209 offset:3088
	ds_read_b128 v[10:13], v209 offset:3600
	v_mov_b32_e32 v26, 0
	s_and_b64 vcc, exec, s[50:51]
	v_mov_b32_e32 v54, 0
	v_mov_b32_e32 v55, 0
	v_mov_b32_e32 v56, 0
	v_mov_b32_e32 v57, 0
	s_cbranch_vccnz .LBB0_403
	ds_read_b128 v[54:57], v240 offset:3600

.LBB0_405:
	s_waitcnt lgkmcnt(4)
	v_cndmask_b32_e64 v77, v109, v77, s[42:43]
	v_cndmask_b32_e64 v76, v105, v76, s[42:43]
	v_cndmask_b32_e64 v75, v101, v75, s[42:43]
	v_cndmask_b32_e64 v74, v97, v74, s[42:43]
	v_pk_mul_f32 v[76:77], v[68:69], v[76:77]
	v_cndmask_b32_e64 v81, v81, v116, s[44:45]
	v_cndmask_b32_e64 v80, v80, v115, s[44:45]
	v_pk_mul_f32 v[74:75], v[66:67], v[74:75]
	v_pk_fma_f32 v[52:53], v[52:53], v[64:65], v[76:77]
	v_cndmask_b32_e64 v79, v79, v114, s[44:45]
	v_cndmask_b32_e64 v78, v78, v112, s[44:45]
	v_pk_fma_f32 v[50:51], v[50:51], v[62:63], v[74:75]
	v_pk_fma_f32 v[52:53], v[60:61], v[80:81], v[52:53]
	v_pk_fma_f32 v[50:51], v[58:59], v[78:79], v[50:51]
	v_pk_add_f32 v[78:79], v[32:33], v[52:53]
	v_cndmask_b32_e64 v53, v98, v101, s[42:43]
	v_cndmask_b32_e64 v52, v95, v97, s[42:43]
	v_pk_add_f32 v[80:81], v[30:31], v[50:51]
	v_cndmask_b32_e64 v51, v106, v109, s[42:43]
	v_cndmask_b32_e64 v50, v102, v105, s[42:43]
	v_pk_mul_f32 v[52:53], v[66:67], v[52:53]
	v_cndmask_b32_e64 v77, v114, v104, s[44:45]
	v_cndmask_b32_e64 v76, v112, v100, s[44:45]
	v_pk_mul_f32 v[50:51], v[68:69], v[50:51]
	v_pk_fma_f32 v[52:53], v[88:89], v[62:63], v[52:53]
	v_cndmask_b32_e64 v75, v116, v111, s[44:45]
	v_cndmask_b32_e64 v74, v115, v108, s[44:45]
	v_pk_fma_f32 v[50:51], v[86:87], v[64:65], v[50:51]
	v_pk_fma_f32 v[52:53], v[58:59], v[76:77], v[52:53]
	v_pk_fma_f32 v[50:51], v[60:61], v[74:75], v[50:51]
	v_pk_add_f32 v[76:77], v[30:31], v[52:53]
	v_cndmask_b32_e64 v53, v90, v98, s[42:43]
	v_cndmask_b32_e64 v52, v0, v95, s[42:43]
	v_pk_add_f32 v[74:75], v[32:33], v[50:51]
	v_cndmask_b32_e64 v51, v94, v106, s[42:43]
	v_cndmask_b32_e64 v50, v92, v102, s[42:43]
	v_pk_mul_f32 v[52:53], v[66:67], v[52:53]
	v_pk_mul_f32 v[50:51], v[68:69], v[50:51]
	v_pk_fma_f32 v[52:53], v[84:85], v[62:63], v[52:53]
	v_cndmask_b32_e64 v85, v107, v90, s[42:43]
	v_cndmask_b32_e64 v84, v103, v0, s[42:43]
	v_pk_fma_f32 v[50:51], v[82:83], v[64:65], v[50:51]
	v_cndmask_b32_e64 v83, v113, v94, s[42:43]
	v_cndmask_b32_e64 v82, v110, v92, s[42:43]
	v_pk_mul_f32 v[66:67], v[66:67], v[84:85]
	v_cndmask_b32_e64 v89, v104, v93, s[44:45]
	v_cndmask_b32_e64 v88, v100, v91, s[44:45]
	v_cndmask_b32_e64 v71, v93, v71, s[44:45]
	v_cndmask_b32_e64 v70, v91, v70, s[44:45]
	v_pk_mul_f32 v[68:69], v[68:69], v[82:83]
	v_pk_fma_f32 v[46:47], v[46:47], v[62:63], v[66:67]
	v_cndmask_b32_e64 v87, v111, v99, s[44:45]
	v_cndmask_b32_e64 v86, v108, v96, s[44:45]
	v_pk_fma_f32 v[52:53], v[58:59], v[88:89], v[52:53]
	v_cndmask_b32_e64 v73, v99, v73, s[44:45]
	v_cndmask_b32_e64 v72, v96, v72, s[44:45]
	v_pk_fma_f32 v[48:49], v[48:49], v[64:65], v[68:69]
	v_pk_fma_f32 v[46:47], v[58:59], v[70:71], v[46:47]
	v_pk_fma_f32 v[50:51], v[60:61], v[86:87], v[50:51]
	v_pk_add_f32 v[52:53], v[30:31], v[52:53]
	v_pk_fma_f32 v[48:49], v[60:61], v[72:73], v[48:49]
	v_pk_add_f32 v[30:31], v[30:31], v[46:47]
	v_mov_b32_e32 v46, v198
	v_mov_b32_e32 v47, v198
	v_pk_fma_f32 v[8:9], v[8:9], v[46:47], v[36:37]
	v_mov_b32_e32 v46, v200
	v_mov_b32_e32 v47, v200
	v_mov_b32_dpp v0, v42 row_ror:1 row_mask:0xf bank_mask:0xf
	v_mov_b32_dpp v58, v43 row_ror:1 row_mask:0xf bank_mask:0xf
	v_mov_b32_dpp v59, v44 row_ror:1 row_mask:0xf bank_mask:0xf
	v_mov_b32_dpp v60, v45 row_ror:1 row_mask:0xf bank_mask:0xf
	v_pk_add_f32 v[50:51], v[32:33], v[50:51]
	v_pk_add_f32 v[32:33], v[32:33], v[48:49]
	v_pk_fma_f32 v[6:7], v[6:7], v[198:199], v[34:35]
	v_pk_fma_f32 v[4:5], v[4:5], v[46:47], v[36:37]
	v_pk_fma_f32 v[2:3], v[2:3], v[200:201], v[34:35]
	s_waitcnt lgkmcnt(0)
	v_cndmask_b32_e64 v35, v58, v55, s[42:43]
	v_cndmask_b32_e64 v34, v0, v54, s[42:43]
	v_cndmask_b32_e64 v37, v60, v57, s[42:43]
	v_cndmask_b32_e64 v36, v59, v56, s[42:43]
	v_mov_b32_dpp v48, v42 row_ror:15 row_mask:0xf bank_mask:0xf
	v_mov_b32_dpp v49, v43 row_ror:15 row_mask:0xf bank_mask:0xf
	v_mov_b32_dpp v46, v44 row_ror:15 row_mask:0xf bank_mask:0xf
	v_mov_b32_dpp v47, v45 row_ror:15 row_mask:0xf bank_mask:0xf
	v_mov_b32_dpp v61, v6 row_ror:15 row_mask:0xf bank_mask:0xf
	v_mov_b32_dpp v62, v7 row_ror:15 row_mask:0xf bank_mask:0xf
	v_mov_b32_dpp v63, v8 row_ror:15 row_mask:0xf bank_mask:0xf
	v_mov_b32_dpp v64, v9 row_ror:15 row_mask:0xf bank_mask:0xf
	v_pk_mul_f32 v[36:37], v[24:25], v[36:37]
	v_pk_mul_f32 v[34:35], v[22:23], v[34:35]
	v_cndmask_b32_e64 v47, v47, v64, s[44:45]
	v_cndmask_b32_e64 v46, v46, v63, s[44:45]
	v_cndmask_b32_e64 v49, v49, v62, s[44:45]
	v_cndmask_b32_e64 v48, v48, v61, s[44:45]
	v_pk_fma_f32 v[34:35], v[42:43], v[18:19], v[34:35]
	v_pk_fma_f32 v[36:37], v[44:45], v[20:21], v[36:37]
	v_pk_fma_f32 v[36:37], v[16:17], v[46:47], v[36:37]
	v_pk_fma_f32 v[34:35], v[14:15], v[48:49], v[34:35]
	v_mov_b32_dpp v54, v6 row_ror:1 row_mask:0xf bank_mask:0xf
	v_mov_b32_dpp v55, v7 row_ror:1 row_mask:0xf bank_mask:0xf
	v_mov_b32_dpp v56, v8 row_ror:1 row_mask:0xf bank_mask:0xf
	v_mov_b32_dpp v57, v9 row_ror:1 row_mask:0xf bank_mask:0xf
	v_pk_add_f32 v[42:43], v[12:13], v[36:37]
	v_pk_add_f32 v[44:45], v[10:11], v[34:35]
	v_cndmask_b32_e64 v35, v57, v60, s[42:43]
	v_cndmask_b32_e64 v34, v56, v59, s[42:43]
	v_cndmask_b32_e64 v37, v55, v58, s[42:43]
	v_cndmask_b32_e64 v36, v54, v0, s[42:43]
	v_mov_b32_dpp v65, v2 row_ror:15 row_mask:0xf bank_mask:0xf
	v_mov_b32_dpp v66, v3 row_ror:15 row_mask:0xf bank_mask:0xf
	v_mov_b32_dpp v67, v4 row_ror:15 row_mask:0xf bank_mask:0xf
	v_mov_b32_dpp v68, v5 row_ror:15 row_mask:0xf bank_mask:0xf
	v_pk_mul_f32 v[34:35], v[24:25], v[34:35]
	v_pk_mul_f32 v[36:37], v[22:23], v[36:37]
	v_cndmask_b32_e64 v47, v64, v68, s[44:45]
	v_cndmask_b32_e64 v46, v63, v67, s[44:45]
	v_cndmask_b32_e64 v49, v62, v66, s[44:45]
	v_cndmask_b32_e64 v48, v61, v65, s[44:45]
	v_pk_fma_f32 v[8:9], v[8:9], v[20:21], v[34:35]
	v_pk_fma_f32 v[6:7], v[6:7], v[18:19], v[36:37]
	v_pk_fma_f32 v[8:9], v[16:17], v[46:47], v[8:9]
	v_pk_fma_f32 v[6:7], v[14:15], v[48:49], v[6:7]
	v_mov_b32_dpp v0, v2 row_ror:1 row_mask:0xf bank_mask:0xf
	v_mov_b32_dpp v58, v3 row_ror:1 row_mask:0xf bank_mask:0xf
	v_mov_b32_dpp v59, v4 row_ror:1 row_mask:0xf bank_mask:0xf
	v_mov_b32_dpp v60, v5 row_ror:1 row_mask:0xf bank_mask:0xf
	v_pk_add_f32 v[34:35], v[12:13], v[8:9]
	v_pk_add_f32 v[36:37], v[10:11], v[6:7]
	v_cndmask_b32_e64 v7, v60, v57, s[42:43]
	v_cndmask_b32_e64 v6, v59, v56, s[42:43]
	v_cndmask_b32_e64 v9, v58, v55, s[42:43]
	v_cndmask_b32_e64 v8, v0, v54, s[42:43]
	v_mov_b32_dpp v61, v38 row_ror:15 row_mask:0xf bank_mask:0xf
	v_mov_b32_dpp v62, v39 row_ror:15 row_mask:0xf bank_mask:0xf
	v_mov_b32_dpp v63, v40 row_ror:15 row_mask:0xf bank_mask:0xf
	v_mov_b32_dpp v64, v41 row_ror:15 row_mask:0xf bank_mask:0xf
	v_pk_mul_f32 v[6:7], v[24:25], v[6:7]
	v_pk_mul_f32 v[8:9], v[22:23], v[8:9]
	v_cndmask_b32_e64 v47, v68, v64, s[44:45]
	v_cndmask_b32_e64 v46, v67, v63, s[44:45]
	v_cndmask_b32_e64 v49, v66, v62, s[44:45]
	v_cndmask_b32_e64 v48, v65, v61, s[44:45]
	v_pk_fma_f32 v[4:5], v[4:5], v[20:21], v[6:7]
	v_pk_fma_f32 v[2:3], v[2:3], v[18:19], v[8:9]
	v_pk_fma_f32 v[4:5], v[16:17], v[46:47], v[4:5]
	v_pk_fma_f32 v[2:3], v[14:15], v[48:49], v[2:3]
	v_pk_add_f32 v[6:7], v[12:13], v[4:5]
	v_pk_add_f32 v[8:9], v[10:11], v[2:3]
	v_mov_b32_dpp v4, v38 row_ror:1 row_mask:0xf bank_mask:0xf
	v_mov_b32_dpp v5, v39 row_ror:1 row_mask:0xf bank_mask:0xf
	v_mov_b32_dpp v2, v40 row_ror:1 row_mask:0xf bank_mask:0xf
	v_mov_b32_dpp v3, v41 row_ror:1 row_mask:0xf bank_mask:0xf
	v_cndmask_b32_e64 v3, v3, v60, s[42:43]
	v_cndmask_b32_e64 v2, v2, v59, s[42:43]
	v_cndmask_b32_e64 v5, v5, v58, s[42:43]
	v_cndmask_b32_e64 v4, v4, v0, s[42:43]
	v_pk_mul_f32 v[2:3], v[24:25], v[2:3]
	v_pk_mul_f32 v[4:5], v[22:23], v[4:5]
	v_cndmask_b32_e64 v27, v62, v27, s[44:45]
	v_cndmask_b32_e64 v26, v61, v26, s[44:45]
	v_cndmask_b32_e64 v29, v64, v29, s[44:45]
	v_cndmask_b32_e64 v28, v63, v28, s[44:45]
	v_pk_fma_f32 v[2:3], v[40:41], v[20:21], v[2:3]
	v_pk_fma_f32 v[4:5], v[38:39], v[18:19], v[4:5]
	v_pk_fma_f32 v[2:3], v[16:17], v[28:29], v[2:3]
	v_pk_fma_f32 v[4:5], v[14:15], v[26:27], v[4:5]
	v_pk_add_f32 v[2:3], v[12:13], v[2:3]
	v_pk_add_f32 v[4:5], v[10:11], v[4:5]
	v_mul_f32_e32 v0, 0xbfb8aa3b, v80
	v_mul_f32_e32 v10, 0xbfb8aa3b, v81
	v_exp_f32_e32 v0, v0
	v_exp_f32_e32 v10, v10
	v_mul_f32_e32 v11, 0xbfb8aa3b, v78
	v_exp_f32_e32 v11, v11
	v_mul_f32_e32 v12, 0xbfb8aa3b, v79
	v_exp_f32_e32 v12, v12
	v_add_f32_e32 v0, 1.0, v0
	v_add_f32_e32 v10, 1.0, v10
	v_rcp_f32_e32 v0, v0
	v_rcp_f32_e32 v10, v10
	v_add_f32_e32 v11, 1.0, v11
	v_rcp_f32_e32 v11, v11
	v_add_f32_e32 v12, 1.0, v12
	v_rcp_f32_e32 v12, v12
	v_mul_f32_e32 v0, v80, v0
	v_mul_f32_e32 v10, v81, v10
	v_mul_f32_e32 v0, v0, v44
	v_mul_f32_e32 v10, v10, v45
	v_mul_f32_e32 v11, v78, v11
	v_mul_f32_e32 v11, v11, v42
	v_mul_f32_e32 v12, v79, v12
	v_cvt_pk_bf16_f32 v10, v0, v10
	v_mov_b32_e32 v0, v150
	v_mul_f32_e32 v12, v12, v43
	v_cvt_pk_bf16_f32 v11, v11, v12
	s_nop 0
	v_add_u32_e32 v0, 0x58004, v0
	v_lshl_add_u64 v[12:13], v[0:1], 1, s[62:63]
	global_store_dwordx2 v[12:13], v[10:11], off
	v_mul_f32_e32 v0, 0xbfb8aa3b, v76
	v_mul_f32_e32 v10, 0xbfb8aa3b, v77
	v_exp_f32_e32 v0, v0
	v_exp_f32_e32 v10, v10
	v_mul_f32_e32 v11, 0xbfb8aa3b, v74
	v_exp_f32_e32 v11, v11
	v_mul_f32_e32 v12, 0xbfb8aa3b, v75
	v_exp_f32_e32 v12, v12
	v_add_f32_e32 v0, 1.0, v0
	v_add_f32_e32 v10, 1.0, v10
	v_rcp_f32_e32 v0, v0
	v_rcp_f32_e32 v10, v10
	v_add_f32_e32 v11, 1.0, v11
	v_rcp_f32_e32 v11, v11
	v_add_f32_e32 v12, 1.0, v12
	v_rcp_f32_e32 v12, v12
	v_mul_f32_e32 v0, v76, v0
	v_mul_f32_e32 v10, v77, v10
	v_mul_f32_e32 v0, v0, v36
	v_mul_f32_e32 v10, v10, v37
	v_mul_f32_e32 v11, v74, v11
	v_mul_f32_e32 v11, v11, v34
	v_mul_f32_e32 v12, v75, v12
	v_cvt_pk_bf16_f32 v10, v0, v10
	v_mov_b32_e32 v0, v150
	v_mul_f32_e32 v12, v12, v35
	v_cvt_pk_bf16_f32 v11, v11, v12
	s_nop 0
	v_add_u32_e32 v0, 0x63004, v0
	v_lshl_add_u64 v[12:13], v[0:1], 1, s[62:63]
	v_mul_f32_e32 v0, 0xbfb8aa3b, v52
	v_exp_f32_e32 v0, v0
	global_store_dwordx2 v[12:13], v[10:11], off
	v_add_f32_e32 v0, 1.0, v0
	v_rcp_f32_e32 v0, v0
	s_nop 0
	v_mul_f32_e32 v0, v52, v0
	v_mul_f32_e32 v0, v0, v8
	v_mul_f32_e32 v8, 0xbfb8aa3b, v53
	v_exp_f32_e32 v8, v8
	s_nop 0
	v_add_f32_e32 v8, 1.0, v8
	v_rcp_f32_e32 v8, v8
	s_nop 0
	v_mul_f32_e32 v8, v53, v8
	v_mul_f32_e32 v8, v8, v9
	v_mul_f32_e32 v9, 0xbfb8aa3b, v50
	v_exp_f32_e32 v9, v9
	s_nop 0
	v_add_f32_e32 v9, 1.0, v9
	v_rcp_f32_e32 v9, v9
	s_nop 0
	v_mul_f32_e32 v9, v50, v9
	v_mul_f32_e32 v9, v9, v6
	v_mul_f32_e32 v6, 0xbfb8aa3b, v51
	v_exp_f32_e32 v6, v6
	s_nop 0
	v_add_f32_e32 v6, 1.0, v6
	v_rcp_f32_e32 v6, v6
	s_nop 0
	v_mul_f32_e32 v6, v51, v6
	v_mul_f32_e32 v7, v6, v7
	v_cvt_pk_bf16_f32 v6, v0, v8
	v_mov_b32_e32 v0, v150
	v_cvt_pk_bf16_f32 v7, v9, v7
	s_nop 0
	v_add_u32_e32 v0, 0x6e004, v0
	v_lshl_add_u64 v[8:9], v[0:1], 1, s[62:63]
	v_mul_f32_e32 v0, 0xbfb8aa3b, v30
	v_exp_f32_e32 v0, v0
	global_store_dwordx2 v[8:9], v[6:7], off
	v_add_f32_e32 v0, 1.0, v0
	v_rcp_f32_e32 v0, v0
	s_nop 0
	v_mul_f32_e32 v0, v30, v0
	v_mul_f32_e32 v0, v0, v4
	v_mul_f32_e32 v4, 0xbfb8aa3b, v31
	v_exp_f32_e32 v4, v4
	s_nop 0
	v_add_f32_e32 v4, 1.0, v4
	v_rcp_f32_e32 v4, v4
	s_nop 0
	v_mul_f32_e32 v4, v31, v4
	v_mul_f32_e32 v4, v4, v5
	v_mul_f32_e32 v5, 0xbfb8aa3b, v32
	v_exp_f32_e32 v5, v5
	s_nop 0
	v_add_f32_e32 v5, 1.0, v5
	v_rcp_f32_e32 v5, v5
	s_nop 0
	v_mul_f32_e32 v5, v32, v5
	v_mul_f32_e32 v5, v5, v2
	v_mul_f32_e32 v2, 0xbfb8aa3b, v33
	v_exp_f32_e32 v2, v2
	s_nop 0
	v_add_f32_e32 v2, 1.0, v2
	v_rcp_f32_e32 v2, v2
	s_nop 0
	v_mul_f32_e32 v2, v33, v2
	v_mul_f32_e32 v3, v2, v3
	v_cvt_pk_bf16_f32 v2, v0, v4
	v_cvt_pk_bf16_f32 v3, v5, v3
	s_nop 0
	v_add_u32_e32 v0, 0x79004, v150
	v_lshl_add_u64 v[4:5], v[0:1], 1, s[62:63]
	global_store_dwordx2 v[4:5], v[2:3], off
	s_andn2_b64 vcc, exec, s[40:41]
	s_mov_b64 s[2:3], -1
	s_cbranch_vccnz .LBB0_319
	s_andn2_b64 vcc, exec, s[26:27]
	s_cbranch_vccnz .LBB0_318
	s_barrier
	s_branch .LBB0_318
